# nt hint: + GLA finish / FNet finish / scan-side streaming loads
# speedup vs baseline: 1.0128x; 1.0023x over previous
.LBB0_1293:
	v_lshl_add_u64 v[36:37], v[6:7], 0, s[4:5]
	v_add_co_u32_e64 v46, s[0:1], s8, v36
	v_add_co_u32_e32 v44, vcc, 0x4aa00000, v36
	s_nop 0
	v_addc_co_u32_e64 v47, s[0:1], 0, v37, s[0:1]
	v_add_co_u32_e64 v38, s[0:1], s9, v36
	v_addc_co_u32_e32 v45, vcc, 0, v37, vcc
	s_nop 0
	v_addc_co_u32_e64 v39, s[0:1], 0, v37, s[0:1]
	v_add_co_u32_e64 v40, s[0:1], s10, v36
	s_add_u32 s4, s4, 0x40000
	s_nop 0
	v_addc_co_u32_e64 v41, s[0:1], 0, v37, s[0:1]
	v_add_co_u32_e64 v42, s[0:1], s11, v36
	s_addc_u32 s5, s5, 0
	s_nop 0
	v_addc_co_u32_e64 v43, s[0:1], 0, v37, s[0:1]
	v_add_co_u32_e64 v48, s[0:1], s12, v36
	s_cmp_eq_u32 s4, 0x400000
	s_nop 0
	v_addc_co_u32_e64 v49, s[0:1], 0, v37, s[0:1]
	v_add_co_u32_e64 v50, s[0:1], s13, v36
	s_nop 1
	v_addc_co_u32_e64 v51, s[0:1], 0, v37, s[0:1]
	v_add_co_u32_e64 v52, s[0:1], s16, v36
	s_nop 1
	v_addc_co_u32_e64 v53, s[0:1], 0, v37, s[0:1]
	global_load_dwordx4 v[12:15], v[38:39], off nt
	global_load_dwordx4 v[16:19], v[40:41], off nt
	global_load_dwordx4 v[20:23], v[42:43], off nt
	global_load_dwordx4 v[24:27], v[48:49], off nt
	global_load_dwordx4 v[28:31], v[50:51], off nt
	global_load_dwordx4 v[32:35], v[52:53], off nt
	global_load_dwordx4 v[36:39], v[44:45], off nt
	s_nop 0
	global_load_dwordx4 v[40:43], v[46:47], off nt
	s_waitcnt vmcnt(7)
	v_lshlrev_b32_e32 v44, 16, v12
	v_and_b32_e32 v45, 0xffff0000, v12
	v_lshlrev_b32_e32 v12, 16, v13
	v_and_b32_e32 v13, 0xffff0000, v13
	v_lshlrev_b32_e32 v46, 16, v14
	s_waitcnt vmcnt(1)
	v_lshlrev_b32_e32 v68, 16, v36
	v_and_b32_e32 v69, 0xffff0000, v36
	v_lshlrev_b32_e32 v36, 16, v37
	v_and_b32_e32 v37, 0xffff0000, v37
	v_lshlrev_b32_e32 v70, 16, v38
	v_and_b32_e32 v71, 0xffff0000, v38
	v_lshlrev_b32_e32 v38, 16, v39
	v_and_b32_e32 v39, 0xffff0000, v39
	s_waitcnt vmcnt(0)
	v_lshlrev_b32_e32 v72, 16, v40
	v_and_b32_e32 v73, 0xffff0000, v40
	v_lshlrev_b32_e32 v40, 16, v41
	v_and_b32_e32 v41, 0xffff0000, v41
	v_lshlrev_b32_e32 v74, 16, v42
	v_and_b32_e32 v75, 0xffff0000, v42
	v_lshlrev_b32_e32 v42, 16, v43
	v_and_b32_e32 v43, 0xffff0000, v43
	v_pk_add_f32 v[10:11], v[10:11], v[68:69]
	v_pk_add_f32 v[8:9], v[8:9], v[36:37]
	v_pk_add_f32 v[4:5], v[4:5], v[70:71]
	v_pk_add_f32 v[2:3], v[2:3], v[38:39]
	v_and_b32_e32 v47, 0xffff0000, v14
	v_lshlrev_b32_e32 v14, 16, v15
	v_and_b32_e32 v15, 0xffff0000, v15
	v_pk_add_f32 v[10:11], v[10:11], v[72:73]
	v_pk_add_f32 v[8:9], v[8:9], v[40:41]
	v_pk_add_f32 v[4:5], v[4:5], v[74:75]
	v_pk_add_f32 v[2:3], v[2:3], v[42:43]
	v_lshlrev_b32_e32 v48, 16, v16
	v_and_b32_e32 v49, 0xffff0000, v16
	v_lshlrev_b32_e32 v16, 16, v17
	v_and_b32_e32 v17, 0xffff0000, v17
	v_lshlrev_b32_e32 v50, 16, v18
	v_and_b32_e32 v51, 0xffff0000, v18
	v_lshlrev_b32_e32 v18, 16, v19
	v_and_b32_e32 v19, 0xffff0000, v19
	v_pk_add_f32 v[10:11], v[10:11], v[44:45]
	v_pk_add_f32 v[8:9], v[8:9], v[12:13]
	v_pk_add_f32 v[4:5], v[4:5], v[46:47]
	v_pk_add_f32 v[2:3], v[2:3], v[14:15]
	v_lshlrev_b32_e32 v52, 16, v20
	v_and_b32_e32 v53, 0xffff0000, v20
	v_lshlrev_b32_e32 v20, 16, v21
	v_and_b32_e32 v21, 0xffff0000, v21
	v_lshlrev_b32_e32 v54, 16, v22
	v_and_b32_e32 v55, 0xffff0000, v22
	v_lshlrev_b32_e32 v22, 16, v23
	v_and_b32_e32 v23, 0xffff0000, v23
	v_pk_add_f32 v[10:11], v[10:11], v[48:49]
	v_pk_add_f32 v[8:9], v[8:9], v[16:17]
	v_pk_add_f32 v[4:5], v[4:5], v[50:51]
	v_pk_add_f32 v[2:3], v[2:3], v[18:19]
	v_lshlrev_b32_e32 v56, 16, v24
	v_and_b32_e32 v57, 0xffff0000, v24
	v_lshlrev_b32_e32 v24, 16, v25
	v_and_b32_e32 v25, 0xffff0000, v25
	v_lshlrev_b32_e32 v58, 16, v26
	v_and_b32_e32 v59, 0xffff0000, v26
	v_lshlrev_b32_e32 v26, 16, v27
	v_and_b32_e32 v27, 0xffff0000, v27
	v_pk_add_f32 v[10:11], v[10:11], v[52:53]
	v_pk_add_f32 v[8:9], v[8:9], v[20:21]
	v_pk_add_f32 v[4:5], v[4:5], v[54:55]
	v_pk_add_f32 v[2:3], v[2:3], v[22:23]
	v_lshlrev_b32_e32 v60, 16, v28
	v_and_b32_e32 v61, 0xffff0000, v28
	v_lshlrev_b32_e32 v28, 16, v29
	v_and_b32_e32 v29, 0xffff0000, v29
	v_lshlrev_b32_e32 v62, 16, v30
	v_and_b32_e32 v63, 0xffff0000, v30
	v_lshlrev_b32_e32 v30, 16, v31
	v_and_b32_e32 v31, 0xffff0000, v31
	v_pk_add_f32 v[10:11], v[10:11], v[56:57]
	v_pk_add_f32 v[8:9], v[8:9], v[24:25]
	v_pk_add_f32 v[4:5], v[4:5], v[58:59]
	v_pk_add_f32 v[2:3], v[2:3], v[26:27]
	v_lshlrev_b32_e32 v64, 16, v32
	v_and_b32_e32 v65, 0xffff0000, v32
	v_lshlrev_b32_e32 v32, 16, v33
	v_and_b32_e32 v33, 0xffff0000, v33
	v_lshlrev_b32_e32 v66, 16, v34
	v_and_b32_e32 v67, 0xffff0000, v34
	v_lshlrev_b32_e32 v34, 16, v35
	v_and_b32_e32 v35, 0xffff0000, v35
	v_pk_add_f32 v[10:11], v[10:11], v[60:61]
	v_pk_add_f32 v[8:9], v[8:9], v[28:29]
	v_pk_add_f32 v[4:5], v[4:5], v[62:63]
	v_pk_add_f32 v[2:3], v[2:3], v[30:31]
	v_pk_add_f32 v[10:11], v[10:11], v[64:65]
	v_pk_add_f32 v[8:9], v[8:9], v[32:33]
	v_pk_add_f32 v[4:5], v[4:5], v[66:67]
	v_pk_add_f32 v[2:3], v[2:3], v[34:35]
	s_cbranch_scc0 .LBB0_1293
	v_mbcnt_lo_u32_b32 v6, -1, 0
	v_mbcnt_hi_u32_b32 v14, -1, v6
	v_and_b32_e32 v7, 64, v14
	v_xor_b32_e32 v6, 8, v14
	v_add_u32_e32 v15, 64, v7
	v_cmp_lt_i32_e32 vcc, v6, v15
	v_and_b32_e32 v1, 8, v0
	v_xor_b32_e32 v16, 32, v14
	v_cndmask_b32_e32 v6, v14, v6, vcc
	v_lshlrev_b32_e32 v17, 2, v6
	v_xor_b32_e32 v6, 16, v14
	v_cmp_lt_i32_e32 vcc, v6, v15
	v_cmp_lt_i32_e64 s[0:1], v16, v15
	s_nop 0
	v_cndmask_b32_e32 v6, v14, v6, vcc
	v_cmp_eq_u32_e32 vcc, 0, v1
	v_lshlrev_b32_e32 v18, 2, v6
	v_cndmask_b32_e64 v1, v14, v16, s[0:1]
	v_cndmask_b32_e64 v7, -v11, v11, vcc
	v_cndmask_b32_e64 v6, -v10, v10, vcc
	v_cndmask_b32_e64 v9, -v9, v9, vcc
	v_cndmask_b32_e64 v8, -v8, v8, vcc
	ds_bpermute_b32 v10, v17, v6
	ds_bpermute_b32 v11, v17, v7
	ds_bpermute_b32 v12, v17, v8
	ds_bpermute_b32 v13, v17, v9
	v_cndmask_b32_e64 v5, -v5, v5, vcc
	v_cndmask_b32_e64 v4, -v4, v4, vcc
	s_waitcnt lgkmcnt(2)
	v_pk_add_f32 v[6:7], v[6:7], v[10:11]
	ds_bpermute_b32 v10, v18, v6
	s_waitcnt lgkmcnt(1)
	v_pk_add_f32 v[12:13], v[8:9], v[12:13]
	ds_bpermute_b32 v11, v18, v7
	ds_bpermute_b32 v14, v18, v12
	ds_bpermute_b32 v15, v18, v13
	v_lshlrev_b32_e32 v1, 2, v1
	s_barrier
	s_waitcnt lgkmcnt(2)
	v_pk_add_f32 v[6:7], v[6:7], v[10:11]
	ds_bpermute_b32 v8, v1, v6
	s_waitcnt lgkmcnt(1)
	v_pk_add_f32 v[10:11], v[12:13], v[14:15]
	v_cndmask_b32_e64 v15, -v3, v3, vcc
	v_cndmask_b32_e64 v14, -v2, v2, vcc
	ds_bpermute_b32 v12, v17, v4
	ds_bpermute_b32 v13, v17, v5
	ds_bpermute_b32 v16, v17, v14
	ds_bpermute_b32 v17, v17, v15
	ds_bpermute_b32 v9, v1, v7
	ds_bpermute_b32 v2, v1, v10
	s_waitcnt lgkmcnt(4)
	v_pk_add_f32 v[4:5], v[4:5], v[12:13]
	ds_bpermute_b32 v12, v18, v4
	s_waitcnt lgkmcnt(3)
	v_pk_add_f32 v[14:15], v[14:15], v[16:17]
	ds_bpermute_b32 v13, v18, v5
	ds_bpermute_b32 v16, v18, v14
	ds_bpermute_b32 v17, v18, v15
	ds_bpermute_b32 v3, v1, v11
	v_cmp_gt_u32_e32 vcc, 8, v162
	s_waitcnt lgkmcnt(3)
	v_pk_add_f32 v[4:5], v[4:5], v[12:13]
	ds_bpermute_b32 v12, v1, v4
	s_waitcnt lgkmcnt(2)
	v_pk_add_f32 v[14:15], v[14:15], v[16:17]
	ds_bpermute_b32 v13, v1, v5
	ds_bpermute_b32 v16, v1, v14
	ds_bpermute_b32 v17, v1, v15
	s_waitcnt lgkmcnt(0)
	s_and_saveexec_b64 s[0:1], vcc
	s_cbranch_execz .LBB0_1296
	s_lshl_b32 s4, s33, 8
	s_add_i32 s4, s4, 0
	v_lshl_add_u32 v1, v162, 5, s4
	v_pk_add_f32 v[6:7], v[6:7], v[8:9]
	v_pk_add_f32 v[8:9], v[10:11], v[2:3]
	v_pk_add_f32 v[2:3], v[4:5], v[12:13]
	v_pk_add_f32 v[4:5], v[14:15], v[16:17]
	ds_write_b128 v1, v[6:9]
	ds_write_b128 v1, v[2:5] offset:16

.LBB0_1302:
	s_mul_hi_u32 s4, s16, 0x3e0f83e1
	s_lshr_b32 s6, s4, 9
	s_mul_i32 s0, s6, 0xfffff7c0
	s_add_i32 s0, s16, s0
	s_cmpk_gt_u32 s0, 0x41f
	s_cselect_b64 s[8:9], -1, 0
	s_add_i32 s1, s0, 0xfbe0
	s_cmpk_lt_u32 s0, 0x420
	s_cselect_b32 s5, s0, s1
	s_and_b32 s10, s5, 15
	s_lshl_b32 s29, s10, 6
	s_and_b32 s0, s29, 0xc0
	v_or_b32_e32 v2, s0, v72
	s_and_b64 s[0:1], s[8:9], exec
	s_cselect_b32 s0, 0x2100000, 0
	s_add_u32 s0, s12, s0
	s_addc_u32 s1, s13, 0
	s_lshl_b32 s10, s10, 8
	s_and_b32 s10, s10, 0xc00
	s_add_u32 s0, s0, s10
	s_addc_u32 s1, s1, 0
	s_and_b32 s4, s4, 0x3ffffe00
	s_add_u32 s0, s0, s4
	s_addc_u32 s1, s1, 0
	v_lshlrev_b32_e32 v66, 1, v2
	v_lshl_add_u64 v[70:71], s[0:1], 0, v[66:67]
	s_lshl_b32 s0, s5, 2
	s_and_b32 s30, s0, 0x1fc0
	v_or_b32_e32 v51, s30, v1
	v_add_u32_e32 v2, -1, v51
	v_cmp_gt_u32_e32 vcc, s17, v51
	s_cmpk_lt_u32 s16, 0x840
	s_cselect_b64 s[0:1], -1, 0
	v_cndmask_b32_e64 v3, 0, 1, vcc
	v_cmp_gt_u32_e32 vcc, s18, v2
	v_mov_b32_e32 v6, 0
	v_mov_b32_e32 v7, 0
	v_cndmask_b32_e64 v2, 0, 1, vcc
	v_cndmask_b32_e64 v2, v2, v3, s[0:1]
	v_and_b32_e32 v2, 1, v2
	v_cmp_eq_u32_e64 s[4:5], 1, v2
	v_mov_b32_e32 v8, 0
	v_mov_b32_e32 v9, 0
	s_and_saveexec_b64 s[10:11], s[4:5]
	s_cbranch_execz .LBB0_1304
	v_lshlrev_b32_e32 v66, 12, v51
	v_lshl_add_u64 v[2:3], v[70:71], 0, v[66:67]
	global_load_dwordx4 v[6:9], v[2:3], off nt
.LBB0_1304:
	s_or_b64 exec, exec, s[10:11]
	v_mov_b32_e32 v2, 0
	v_mov_b32_e32 v14, 0
	v_mov_b32_e32 v15, 0
	v_mov_b32_e32 v16, 0
	v_mov_b32_e32 v17, 0
	s_and_saveexec_b64 s[4:5], vcc
	s_cbranch_execz .LBB0_1306
	v_lshlrev_b32_e32 v3, 11, v51
	v_sub_u32_e32 v3, 0x1000000, v3
	v_lshlrev_b32_e32 v66, 1, v3
	v_lshl_add_u64 v[4:5], v[70:71], 0, v[66:67]
	global_load_dwordx4 v[14:17], v[4:5], off nt
.LBB0_1306:
	s_or_b64 exec, exec, s[4:5]
	s_and_b32 s30, 0xffff, s30
	s_cmpk_lt_u32 s30, 0xff8
	v_cmp_gt_u32_e32 vcc, s19, v51
	s_cselect_b64 s[4:5], -1, 0
	v_cndmask_b32_e64 v4, 0, 1, s[4:5]
	v_cndmask_b32_e64 v3, 0, 1, vcc
	v_cndmask_b32_e64 v3, v4, v3, s[0:1]
	v_and_b32_e32 v3, 1, v3
	v_or_b32_e32 v11, 8, v51
	v_cmp_eq_u32_e32 vcc, 1, v3
	v_mov_b32_e32 v3, 0
	v_mov_b32_e32 v4, 0
	v_mov_b32_e32 v5, 0
	s_and_saveexec_b64 s[10:11], vcc
	s_cbranch_execz .LBB0_1308
	v_lshlrev_b32_e32 v66, 12, v11
	v_lshl_add_u64 v[2:3], v[70:71], 0, v[66:67]
	global_load_dwordx4 v[2:5], v[2:3], off nt
.LBB0_1308:
	s_or_b64 exec, exec, s[10:11]
	v_mov_b32_e32 v10, 0
	s_andn2_b64 vcc, exec, s[4:5]
	v_mov_b32_e32 v22, 0
	v_mov_b32_e32 v23, 0
	v_mov_b32_e32 v24, 0
	v_mov_b32_e32 v25, 0
	s_cbranch_vccnz .LBB0_1310
	v_lshlrev_b32_e32 v11, 11, v11
	v_sub_u32_e32 v11, 0x1000000, v11
	v_lshlrev_b32_e32 v66, 1, v11
	v_lshl_add_u64 v[12:13], v[70:71], 0, v[66:67]
	global_load_dwordx4 v[22:25], v[12:13], off nt
.LBB0_1310:
	s_cmpk_lt_u32 s30, 0xff0
	v_cmp_gt_u32_e32 vcc, s22, v51
	s_cselect_b64 s[4:5], -1, 0
	v_cndmask_b32_e64 v12, 0, 1, s[4:5]
	v_cndmask_b32_e64 v11, 0, 1, vcc
	v_cndmask_b32_e64 v11, v12, v11, s[0:1]
	v_and_b32_e32 v11, 1, v11
	v_or_b32_e32 v19, 16, v51
	v_cmp_eq_u32_e32 vcc, 1, v11
	v_mov_b32_e32 v11, 0
	v_mov_b32_e32 v12, 0
	v_mov_b32_e32 v13, 0
	s_and_saveexec_b64 s[10:11], vcc
	s_cbranch_execz .LBB0_1312
	v_lshlrev_b32_e32 v66, 12, v19
	v_lshl_add_u64 v[10:11], v[70:71], 0, v[66:67]
	global_load_dwordx4 v[10:13], v[10:11], off nt
.LBB0_1312:
	s_or_b64 exec, exec, s[10:11]
	v_mov_b32_e32 v18, 0
	s_andn2_b64 vcc, exec, s[4:5]
	v_mov_b32_e32 v30, 0
	v_mov_b32_e32 v31, 0
	v_mov_b32_e32 v32, 0
	v_mov_b32_e32 v33, 0
	s_cbranch_vccnz .LBB0_1314
	v_lshlrev_b32_e32 v19, 11, v19
	v_sub_u32_e32 v19, 0x1000000, v19
	v_lshlrev_b32_e32 v66, 1, v19
	v_lshl_add_u64 v[20:21], v[70:71], 0, v[66:67]
	global_load_dwordx4 v[30:33], v[20:21], off nt
.LBB0_1314:
	s_cmpk_lt_u32 s30, 0xfe8
	v_cmp_gt_u32_e32 vcc, s23, v51
	s_cselect_b64 s[4:5], -1, 0
	v_cndmask_b32_e64 v20, 0, 1, s[4:5]
	v_cndmask_b32_e64 v19, 0, 1, vcc
	v_cndmask_b32_e64 v19, v20, v19, s[0:1]
	v_and_b32_e32 v19, 1, v19
	v_or_b32_e32 v27, 24, v51
	v_cmp_eq_u32_e32 vcc, 1, v19
	v_mov_b32_e32 v19, 0
	v_mov_b32_e32 v20, 0
	v_mov_b32_e32 v21, 0
	s_and_saveexec_b64 s[10:11], vcc
	s_cbranch_execz .LBB0_1316
	v_lshlrev_b32_e32 v66, 12, v27
	v_lshl_add_u64 v[18:19], v[70:71], 0, v[66:67]
	global_load_dwordx4 v[18:21], v[18:19], off nt
.LBB0_1316:
	s_or_b64 exec, exec, s[10:11]
	v_mov_b32_e32 v26, 0
	s_andn2_b64 vcc, exec, s[4:5]
	v_mov_b32_e32 v38, 0
	v_mov_b32_e32 v39, 0
	v_mov_b32_e32 v40, 0
	v_mov_b32_e32 v41, 0
	s_cbranch_vccnz .LBB0_1318
	v_lshlrev_b32_e32 v27, 11, v27
	v_sub_u32_e32 v27, 0x1000000, v27
	v_lshlrev_b32_e32 v66, 1, v27
	v_lshl_add_u64 v[28:29], v[70:71], 0, v[66:67]
	global_load_dwordx4 v[38:41], v[28:29], off nt
.LBB0_1318:
	s_cmpk_lt_u32 s30, 0xfe0
	v_cmp_gt_u32_e32 vcc, s24, v51
	s_cselect_b64 s[4:5], -1, 0
	v_cndmask_b32_e64 v28, 0, 1, s[4:5]
	v_cndmask_b32_e64 v27, 0, 1, vcc
	v_cndmask_b32_e64 v27, v28, v27, s[0:1]
	v_and_b32_e32 v27, 1, v27
	v_or_b32_e32 v35, 32, v51
	v_cmp_eq_u32_e32 vcc, 1, v27
	v_mov_b32_e32 v27, 0
	v_mov_b32_e32 v28, 0
	v_mov_b32_e32 v29, 0
	s_and_saveexec_b64 s[10:11], vcc
	s_cbranch_execz .LBB0_1320
	v_lshlrev_b32_e32 v66, 12, v35
	v_lshl_add_u64 v[26:27], v[70:71], 0, v[66:67]
	global_load_dwordx4 v[26:29], v[26:27], off nt
.LBB0_1320:
	s_or_b64 exec, exec, s[10:11]
	v_mov_b32_e32 v34, 0
	s_andn2_b64 vcc, exec, s[4:5]
	v_mov_b32_e32 v46, 0
	v_mov_b32_e32 v47, 0
	v_mov_b32_e32 v48, 0
	v_mov_b32_e32 v49, 0
	s_cbranch_vccnz .LBB0_1322
	v_lshlrev_b32_e32 v35, 11, v35
	v_sub_u32_e32 v35, 0x1000000, v35
	v_lshlrev_b32_e32 v66, 1, v35
	v_lshl_add_u64 v[36:37], v[70:71], 0, v[66:67]
	global_load_dwordx4 v[46:49], v[36:37], off nt
.LBB0_1322:
	s_cmpk_lt_u32 s30, 0xfd8
	v_cmp_gt_u32_e32 vcc, s25, v51
	s_cselect_b64 s[4:5], -1, 0
	v_cndmask_b32_e64 v36, 0, 1, s[4:5]
	v_cndmask_b32_e64 v35, 0, 1, vcc
	v_cndmask_b32_e64 v35, v36, v35, s[0:1]
	v_and_b32_e32 v35, 1, v35
	v_or_b32_e32 v43, 40, v51
	v_cmp_eq_u32_e32 vcc, 1, v35
	v_mov_b32_e32 v35, 0
	v_mov_b32_e32 v36, 0
	v_mov_b32_e32 v37, 0
	s_and_saveexec_b64 s[10:11], vcc
	s_cbranch_execz .LBB0_1324
	v_lshlrev_b32_e32 v66, 12, v43
	v_lshl_add_u64 v[34:35], v[70:71], 0, v[66:67]
	global_load_dwordx4 v[34:37], v[34:35], off nt
.LBB0_1324:
	s_or_b64 exec, exec, s[10:11]
	v_mov_b32_e32 v42, 0
	s_andn2_b64 vcc, exec, s[4:5]
	v_mov_b32_e32 v54, 0
	v_mov_b32_e32 v55, 0
	v_mov_b32_e32 v56, 0
	v_mov_b32_e32 v57, 0
	s_cbranch_vccnz .LBB0_1326
	v_lshlrev_b32_e32 v43, 11, v43
	v_sub_u32_e32 v43, 0x1000000, v43
	v_lshlrev_b32_e32 v66, 1, v43
	v_lshl_add_u64 v[44:45], v[70:71], 0, v[66:67]
	global_load_dwordx4 v[54:57], v[44:45], off nt
.LBB0_1326:
	s_cmpk_lt_u32 s30, 0xfd0
	v_cmp_gt_u32_e32 vcc, s26, v51
	s_cselect_b64 s[4:5], -1, 0
	v_cndmask_b32_e64 v44, 0, 1, s[4:5]
	v_cndmask_b32_e64 v43, 0, 1, vcc
	v_cndmask_b32_e64 v43, v44, v43, s[0:1]
	v_and_b32_e32 v43, 1, v43
	v_or_b32_e32 v52, 48, v51
	v_cmp_eq_u32_e32 vcc, 1, v43
	v_mov_b32_e32 v43, 0
	v_mov_b32_e32 v44, 0
	v_mov_b32_e32 v45, 0
	s_and_saveexec_b64 s[10:11], vcc
	s_cbranch_execz .LBB0_1328
	v_lshlrev_b32_e32 v66, 12, v52
	v_lshl_add_u64 v[42:43], v[70:71], 0, v[66:67]
	global_load_dwordx4 v[42:45], v[42:43], off nt
.LBB0_1328:
	s_or_b64 exec, exec, s[10:11]
	v_mov_b32_e32 v50, 0
	s_andn2_b64 vcc, exec, s[4:5]
	v_mov_b32_e32 v58, 0
	v_mov_b32_e32 v59, 0
	v_mov_b32_e32 v60, 0
	v_mov_b32_e32 v61, 0
	s_cbranch_vccnz .LBB0_1330
	v_lshlrev_b32_e32 v52, 11, v52
	v_sub_u32_e32 v52, 0x1000000, v52
	v_lshlrev_b32_e32 v66, 1, v52
	v_lshl_add_u64 v[52:53], v[70:71], 0, v[66:67]
	global_load_dwordx4 v[58:61], v[52:53], off nt
.LBB0_1330:
	s_cmpk_lt_u32 s30, 0xfc8
	v_cmp_gt_u32_e32 vcc, s27, v51
	s_cselect_b64 s[4:5], -1, 0
	v_or_b32_e32 v82, 56, v51
	v_cndmask_b32_e64 v51, 0, 1, vcc
	v_cndmask_b32_e64 v52, 0, 1, s[4:5]
	v_cndmask_b32_e64 v51, v52, v51, s[0:1]
	v_and_b32_e32 v51, 1, v51
	v_cmp_eq_u32_e32 vcc, 1, v51
	v_mov_b32_e32 v51, 0
	v_mov_b32_e32 v52, 0
	v_mov_b32_e32 v53, 0
	s_and_saveexec_b64 s[10:11], vcc
	s_cbranch_execz .LBB0_1332
	v_lshlrev_b32_e32 v66, 12, v82
	v_lshl_add_u64 v[50:51], v[70:71], 0, v[66:67]
	global_load_dwordx4 v[50:53], v[50:51], off nt
.LBB0_1332:
	s_or_b64 exec, exec, s[10:11]
	v_mov_b32_e32 v62, 0
	s_andn2_b64 vcc, exec, s[4:5]
	v_mov_b32_e32 v63, 0
	v_mov_b32_e32 v64, 0
	v_mov_b32_e32 v65, 0
	s_cbranch_vccnz .LBB0_1301
	v_lshlrev_b32_e32 v62, 11, v82
	v_sub_u32_e32 v62, 0x1000000, v62
	v_lshlrev_b32_e32 v66, 1, v62
	v_lshl_add_u64 v[62:63], v[70:71], 0, v[66:67]
	global_load_dwordx4 v[62:65], v[62:63], off nt
	s_branch .LBB0_1301

.LBB0_1378:
	s_ashr_i32 s1, s0, 7
	s_lshl_b32 s0, s1, 6
	s_lshl_b32 s1, s1, 12
	s_sub_i32 s10, s9, s1
	v_add_u32_e32 v2, s10, v1
	v_lshl_add_u64 v[6:7], v[2:3], 2, s[82:83]
	v_mov_b32_e32 v2, 0
	s_andn2_b64 vcc, exec, s[6:7]
	v_mov_b32_e32 v47, 0
	s_cbranch_vccnz .LBB0_1404
	v_or_b32_e32 v48, s0, v8
	v_ashrrev_i32_e32 v49, 31, v48
	v_or_b32_e32 v50, s0, v9
	v_or_b32_e32 v52, s0, v10
	v_or_b32_e32 v54, s0, v11
	v_lshlrev_b64 v[48:49], 14, v[48:49]
	v_ashrrev_i32_e32 v51, 31, v50
	v_ashrrev_i32_e32 v53, 31, v52
	v_ashrrev_i32_e32 v55, 31, v54
	v_lshl_add_u64 v[48:49], v[6:7], 0, v[48:49]
	v_lshlrev_b64 v[50:51], 14, v[50:51]
	v_lshlrev_b64 v[52:53], 14, v[52:53]
	v_lshlrev_b64 v[54:55], 14, v[54:55]
	v_lshl_add_u64 v[50:51], v[6:7], 0, v[50:51]
	v_lshl_add_u64 v[52:53], v[6:7], 0, v[52:53]
	v_lshl_add_u64 v[54:55], v[6:7], 0, v[54:55]
	global_load_dword v56, v[48:49], off nt
	global_load_dword v57, v[50:51], off nt
	global_load_dword v2, v[52:53], off nt
	global_load_dword v47, v[54:55], off nt
	s_waitcnt vmcnt(2)
	ds_write2_b32 v42, v56, v57 offset1:66
	s_mov_b64 s[6:7], -1
	s_and_b64 vcc, exec, s[4:5]
	s_waitcnt vmcnt(0)
	ds_write2_b32 v43, v2, v47 offset1:66
	s_cbranch_vccnz .LBB0_1405

.LBB0_1381:
	v_or_b32_e32 v48, s0, v12
	v_ashrrev_i32_e32 v49, 31, v48
	v_or_b32_e32 v50, s0, v13
	v_or_b32_e32 v52, s0, v14
	v_or_b32_e32 v54, s0, v15
	v_lshlrev_b64 v[48:49], 14, v[48:49]
	v_ashrrev_i32_e32 v51, 31, v50
	v_ashrrev_i32_e32 v53, 31, v52
	v_ashrrev_i32_e32 v55, 31, v54
	v_lshl_add_u64 v[48:49], v[6:7], 0, v[48:49]
	v_lshlrev_b64 v[50:51], 14, v[50:51]
	v_lshlrev_b64 v[52:53], 14, v[52:53]
	v_lshlrev_b64 v[54:55], 14, v[54:55]
	v_lshl_add_u64 v[50:51], v[6:7], 0, v[50:51]
	v_lshl_add_u64 v[52:53], v[6:7], 0, v[52:53]
	v_lshl_add_u64 v[54:55], v[6:7], 0, v[54:55]
	global_load_dword v56, v[48:49], off nt
	global_load_dword v57, v[50:51], off nt
	global_load_dword v2, v[52:53], off nt
	global_load_dword v47, v[54:55], off nt
	s_waitcnt vmcnt(2)
	ds_write2_b32 v44, v56, v57 offset1:66
	s_mov_b64 s[6:7], -1
	s_and_b64 vcc, exec, s[4:5]
	s_waitcnt vmcnt(0)
	ds_write2_b32 v45, v2, v47 offset1:66
	s_cbranch_vccnz .LBB0_1407

.LBB0_1383:
	v_or_b32_e32 v48, s0, v16
	v_ashrrev_i32_e32 v49, 31, v48
	v_or_b32_e32 v50, s0, v17
	v_or_b32_e32 v52, s0, v18
	v_or_b32_e32 v54, s0, v19
	v_lshlrev_b64 v[48:49], 14, v[48:49]
	v_ashrrev_i32_e32 v51, 31, v50
	v_ashrrev_i32_e32 v53, 31, v52
	v_ashrrev_i32_e32 v55, 31, v54
	v_lshl_add_u64 v[48:49], v[6:7], 0, v[48:49]
	v_lshlrev_b64 v[50:51], 14, v[50:51]
	v_lshlrev_b64 v[52:53], 14, v[52:53]
	v_lshlrev_b64 v[54:55], 14, v[54:55]
	v_lshl_add_u64 v[50:51], v[6:7], 0, v[50:51]
	v_lshl_add_u64 v[52:53], v[6:7], 0, v[52:53]
	v_lshl_add_u64 v[54:55], v[6:7], 0, v[54:55]
	global_load_dword v56, v[48:49], off nt
	global_load_dword v57, v[50:51], off nt
	global_load_dword v2, v[52:53], off nt
	global_load_dword v47, v[54:55], off nt
	s_waitcnt vmcnt(2)
	ds_write2_b32 v46, v56, v57 offset1:66

.LBB0_1386:
	v_mov_b32_e32 v47, 0
	s_andn2_b64 vcc, exec, s[6:7]
	v_mov_b32_e32 v48, 0
	s_cbranch_vccnz .LBB0_1388
	v_or_b32_e32 v48, s0, v20
	v_ashrrev_i32_e32 v49, 31, v48
	v_lshlrev_b64 v[48:49], 14, v[48:49]
	v_lshl_add_u64 v[50:51], v[6:7], 0, v[48:49]
	v_or_b32_e32 v48, s0, v21
	v_ashrrev_i32_e32 v49, 31, v48
	v_lshlrev_b64 v[48:49], 14, v[48:49]
	v_lshl_add_u64 v[52:53], v[6:7], 0, v[48:49]
	v_or_b32_e32 v48, s0, v22
	v_ashrrev_i32_e32 v49, 31, v48
	v_lshlrev_b64 v[48:49], 14, v[48:49]
	v_lshl_add_u64 v[54:55], v[6:7], 0, v[48:49]
	v_or_b32_e32 v48, s0, v23
	v_ashrrev_i32_e32 v49, 31, v48
	v_lshlrev_b64 v[48:49], 14, v[48:49]
	v_lshl_add_u64 v[56:57], v[6:7], 0, v[48:49]
	global_load_dword v49, v[50:51], off nt
	global_load_dword v58, v[52:53], off nt
	global_load_dword v47, v[54:55], off nt
	global_load_dword v48, v[56:57], off nt
	s_waitcnt vmcnt(2)
	ds_write2_b32 v2, v49, v58 offset0:8 offset1:74

.LBB0_1390:
	v_mov_b32_e32 v47, 0
	s_andn2_b64 vcc, exec, s[6:7]
	v_mov_b32_e32 v48, 0
	s_cbranch_vccnz .LBB0_1392
	v_or_b32_e32 v48, s0, v24
	v_ashrrev_i32_e32 v49, 31, v48
	v_lshlrev_b64 v[48:49], 14, v[48:49]
	v_lshl_add_u64 v[50:51], v[6:7], 0, v[48:49]
	v_or_b32_e32 v48, s0, v25
	v_ashrrev_i32_e32 v49, 31, v48
	v_lshlrev_b64 v[48:49], 14, v[48:49]
	v_lshl_add_u64 v[52:53], v[6:7], 0, v[48:49]
	v_or_b32_e32 v48, s0, v26
	v_ashrrev_i32_e32 v49, 31, v48
	v_lshlrev_b64 v[48:49], 14, v[48:49]
	v_lshl_add_u64 v[54:55], v[6:7], 0, v[48:49]
	v_or_b32_e32 v48, s0, v27
	v_ashrrev_i32_e32 v49, 31, v48
	v_lshlrev_b64 v[48:49], 14, v[48:49]
	v_lshl_add_u64 v[56:57], v[6:7], 0, v[48:49]
	global_load_dword v49, v[50:51], off nt
	global_load_dword v58, v[52:53], off nt
	global_load_dword v47, v[54:55], off nt
	global_load_dword v48, v[56:57], off nt
	s_waitcnt vmcnt(2)
	ds_write2_b32 v2, v49, v58 offset0:16 offset1:82

.LBB0_1394:
	v_mov_b32_e32 v47, 0
	s_andn2_b64 vcc, exec, s[6:7]
	v_mov_b32_e32 v48, 0
	s_cbranch_vccnz .LBB0_1396
	v_or_b32_e32 v48, s0, v28
	v_ashrrev_i32_e32 v49, 31, v48
	v_lshlrev_b64 v[48:49], 14, v[48:49]
	v_lshl_add_u64 v[50:51], v[6:7], 0, v[48:49]
	v_or_b32_e32 v48, s0, v29
	v_ashrrev_i32_e32 v49, 31, v48
	v_lshlrev_b64 v[48:49], 14, v[48:49]
	v_lshl_add_u64 v[52:53], v[6:7], 0, v[48:49]
	v_or_b32_e32 v48, s0, v30
	v_ashrrev_i32_e32 v49, 31, v48
	v_lshlrev_b64 v[48:49], 14, v[48:49]
	v_lshl_add_u64 v[54:55], v[6:7], 0, v[48:49]
	v_or_b32_e32 v48, s0, v31
	v_ashrrev_i32_e32 v49, 31, v48
	v_lshlrev_b64 v[48:49], 14, v[48:49]
	v_lshl_add_u64 v[56:57], v[6:7], 0, v[48:49]
	global_load_dword v49, v[50:51], off nt
	global_load_dword v58, v[52:53], off nt
	global_load_dword v47, v[54:55], off nt
	global_load_dword v48, v[56:57], off nt
	s_waitcnt vmcnt(2)
	ds_write2_b32 v2, v49, v58 offset0:24 offset1:90

.LBB0_1398:
	v_mov_b32_e32 v47, 0
	s_andn2_b64 vcc, exec, s[6:7]
	v_mov_b32_e32 v48, 0
	s_cbranch_vccnz .LBB0_1400
	v_or_b32_e32 v48, s0, v32
	v_ashrrev_i32_e32 v49, 31, v48
	v_lshlrev_b64 v[48:49], 14, v[48:49]
	v_lshl_add_u64 v[50:51], v[6:7], 0, v[48:49]
	v_or_b32_e32 v48, s0, v33
	v_ashrrev_i32_e32 v49, 31, v48
	v_lshlrev_b64 v[48:49], 14, v[48:49]
	v_lshl_add_u64 v[52:53], v[6:7], 0, v[48:49]
	v_or_b32_e32 v48, s0, v34
	v_ashrrev_i32_e32 v49, 31, v48
	v_lshlrev_b64 v[48:49], 14, v[48:49]
	v_lshl_add_u64 v[54:55], v[6:7], 0, v[48:49]
	v_or_b32_e32 v48, s0, v35
	v_ashrrev_i32_e32 v49, 31, v48
	v_lshlrev_b64 v[48:49], 14, v[48:49]
	v_lshl_add_u64 v[56:57], v[6:7], 0, v[48:49]
	global_load_dword v49, v[50:51], off nt
	global_load_dword v58, v[52:53], off nt
	global_load_dword v47, v[54:55], off nt
	global_load_dword v48, v[56:57], off nt
	s_waitcnt vmcnt(2)
	ds_write2_b32 v2, v49, v58 offset0:32 offset1:98

.LBB0_1402:
	v_mov_b32_e32 v47, 0
	s_andn2_b64 vcc, exec, s[6:7]
	v_mov_b32_e32 v48, 0
	s_cbranch_vccnz .LBB0_1375
	v_or_b32_e32 v48, s0, v36
	v_ashrrev_i32_e32 v49, 31, v48
	v_lshlrev_b64 v[48:49], 14, v[48:49]
	v_lshl_add_u64 v[50:51], v[6:7], 0, v[48:49]
	v_or_b32_e32 v48, s0, v37
	v_ashrrev_i32_e32 v49, 31, v48
	v_lshlrev_b64 v[48:49], 14, v[48:49]
	v_lshl_add_u64 v[52:53], v[6:7], 0, v[48:49]
	v_or_b32_e32 v48, s0, v38
	v_ashrrev_i32_e32 v49, 31, v48
	v_lshlrev_b64 v[48:49], 14, v[48:49]
	v_lshl_add_u64 v[54:55], v[6:7], 0, v[48:49]
	v_or_b32_e32 v48, s0, v39
	v_ashrrev_i32_e32 v49, 31, v48
	v_lshlrev_b64 v[48:49], 14, v[48:49]
	v_lshl_add_u64 v[6:7], v[6:7], 0, v[48:49]
	global_load_dword v49, v[50:51], off nt
	global_load_dword v56, v[52:53], off nt
	global_load_dword v47, v[54:55], off nt
	global_load_dword v48, v[6:7], off nt
	s_waitcnt vmcnt(2)
	ds_write2_b32 v2, v49, v56 offset0:40 offset1:106
	s_branch .LBB0_1375

.LBB0_1593:
	s_add_u32 s4, s92, 0x4ec00000
	s_addc_u32 s5, s93, 0
	s_ashr_i32 s1, s0, 31
	v_lshl_add_u32 v130, s20, 8, v142
	v_mov_b32_e32 v131, 0
	s_lshl_b64 s[0:1], s[0:1], 24
	v_lshlrev_b64 v[132:133], 12, v[130:131]
	v_lshl_or_b32 v1, s21, 8, v1
	v_lshl_add_u64 v[132:133], v[132:133], 0, s[0:1]
	s_mov_b32 s0, 0x3a3504f3
	v_or_b32_e32 v1, s26, v1
	v_pk_mul_f32 v[126:127], v[126:127], s[0:1] op_sel_hi:[1,0]
	v_pk_mul_f32 v[122:123], v[122:123], s[0:1] op_sel_hi:[1,0]
	v_pk_mul_f32 v[128:129], v[128:129], s[0:1] op_sel_hi:[1,0]
	v_pk_mul_f32 v[134:135], v[124:125], s[0:1] op_sel_hi:[1,0]
	v_cvt_pk_bf16_f32 v124, v126, v127
	v_cvt_pk_bf16_f32 v125, v128, v129
	v_cvt_pk_bf16_f32 v126, v122, v123
	v_lshl_add_u64 v[122:123], s[4:5], 0, v[132:133]
	v_lshlrev_b32_e32 v130, 1, v1
	v_lshl_add_u64 v[122:123], v[122:123], 0, v[130:131]
	v_cvt_pk_bf16_f32 v127, v134, v135
	global_store_dwordx4 v[122:123], v[124:127], off
	v_pk_mul_f32 v[120:121], v[120:121], s[0:1] op_sel_hi:[1,0]
	v_pk_mul_f32 v[118:119], v[118:119], s[0:1] op_sel_hi:[1,0]
	v_pk_mul_f32 v[124:125], v[112:113], s[0:1] op_sel_hi:[1,0]
	v_pk_mul_f32 v[112:113], v[110:111], s[0:1] op_sel_hi:[1,0]
	v_cvt_pk_bf16_f32 v110, v118, v119
	v_cvt_pk_bf16_f32 v111, v120, v121
	v_pk_mul_f32 v[114:115], v[114:115], s[0:1] op_sel_hi:[1,0]
	v_cvt_pk_bf16_f32 v112, v112, v113
	v_cvt_pk_bf16_f32 v113, v124, v125
	global_store_dwordx4 v[122:123], v[110:113], off offset:256
	v_pk_mul_f32 v[104:105], v[104:105], s[0:1] op_sel_hi:[1,0]
	v_pk_mul_f32 v[102:103], v[102:103], s[0:1] op_sel_hi:[1,0]
	v_or_b32_e32 v110, 0x10000, v132
	v_mov_b32_e32 v111, v133
	v_lshl_add_u64 v[110:111], s[4:5], 0, v[110:111]
	v_pk_mul_f32 v[112:113], v[116:117], s[0:1] op_sel_hi:[1,0]
	v_pk_mul_f32 v[116:117], v[108:109], s[0:1] op_sel_hi:[1,0]
	v_pk_mul_f32 v[108:109], v[106:107], s[0:1] op_sel_hi:[1,0]
	v_cvt_pk_bf16_f32 v106, v114, v115
	v_cvt_pk_bf16_f32 v107, v112, v113
	v_lshl_add_u64 v[110:111], v[110:111], 0, v[130:131]
	v_cvt_pk_bf16_f32 v108, v108, v109
	v_cvt_pk_bf16_f32 v109, v116, v117
	global_store_dwordx4 v[110:111], v[106:109], off
	v_pk_mul_f32 v[98:99], v[98:99], s[0:1] op_sel_hi:[1,0]
	v_pk_mul_f32 v[88:89], v[88:89], s[0:1] op_sel_hi:[1,0]
	v_pk_mul_f32 v[106:107], v[96:97], s[0:1] op_sel_hi:[1,0]
	v_pk_mul_f32 v[96:97], v[94:95], s[0:1] op_sel_hi:[1,0]
	v_cvt_pk_bf16_f32 v94, v102, v103
	v_cvt_pk_bf16_f32 v95, v104, v105
	v_pk_mul_f32 v[86:87], v[86:87], s[0:1] op_sel_hi:[1,0]
	v_cvt_pk_bf16_f32 v96, v96, v97
	v_cvt_pk_bf16_f32 v97, v106, v107
	global_store_dwordx4 v[110:111], v[94:97], off offset:256
	v_pk_mul_f32 v[72:73], v[72:73], s[0:1] op_sel_hi:[1,0]
	v_pk_mul_f32 v[70:71], v[70:71], s[0:1] op_sel_hi:[1,0]
	v_or_b32_e32 v94, 0x20000, v132
	v_mov_b32_e32 v95, v133
	v_lshl_add_u64 v[94:95], s[4:5], 0, v[94:95]
	v_pk_mul_f32 v[96:97], v[100:101], s[0:1] op_sel_hi:[1,0]
	v_pk_mul_f32 v[100:101], v[92:93], s[0:1] op_sel_hi:[1,0]
	v_pk_mul_f32 v[92:93], v[90:91], s[0:1] op_sel_hi:[1,0]
	v_cvt_pk_bf16_f32 v90, v98, v99
	v_cvt_pk_bf16_f32 v91, v96, v97
	v_lshl_add_u64 v[94:95], v[94:95], 0, v[130:131]
	v_cvt_pk_bf16_f32 v92, v92, v93
	v_cvt_pk_bf16_f32 v93, v100, v101
	global_store_dwordx4 v[94:95], v[90:93], off
	v_or_b32_e32 v132, 0x30000, v132
	v_pk_mul_f32 v[64:65], v[64:65], s[0:1] op_sel_hi:[1,0]
	v_pk_mul_f32 v[90:91], v[80:81], s[0:1] op_sel_hi:[1,0]
	v_pk_mul_f32 v[80:81], v[78:79], s[0:1] op_sel_hi:[1,0]
	v_cvt_pk_bf16_f32 v78, v86, v87
	v_cvt_pk_bf16_f32 v79, v88, v89
	v_pk_mul_f32 v[62:63], v[62:63], s[0:1] op_sel_hi:[1,0]
	v_cvt_pk_bf16_f32 v80, v80, v81
	v_cvt_pk_bf16_f32 v81, v90, v91
	global_store_dwordx4 v[94:95], v[78:81], off offset:256
	s_cmpk_gt_u32 s57, 0xfff
	s_nop 0
	v_pk_mul_f32 v[78:79], v[84:85], s[0:1] op_sel_hi:[1,0]
	v_pk_mul_f32 v[80:81], v[82:83], s[0:1] op_sel_hi:[1,0]
	v_pk_mul_f32 v[82:83], v[76:77], s[0:1] op_sel_hi:[1,0]
	v_pk_mul_f32 v[76:77], v[74:75], s[0:1] op_sel_hi:[1,0]
	v_cvt_pk_bf16_f32 v74, v80, v81
	v_cvt_pk_bf16_f32 v75, v78, v79
	v_lshl_add_u64 v[78:79], s[4:5], 0, v[132:133]
	v_lshl_add_u64 v[78:79], v[78:79], 0, v[130:131]
	v_cvt_pk_bf16_f32 v76, v76, v77
	v_cvt_pk_bf16_f32 v77, v82, v83
	global_store_dwordx4 v[78:79], v[74:77], off
	s_mov_b64 s[4:5], 0x80000
	s_nop 0
	v_pk_mul_f32 v[74:75], v[68:69], s[0:1] op_sel_hi:[1,0]
	v_pk_mul_f32 v[68:69], v[66:67], s[0:1] op_sel_hi:[1,0]
	v_cvt_pk_bf16_f32 v66, v70, v71
	v_cvt_pk_bf16_f32 v67, v72, v73
	s_nop 0
	v_cvt_pk_bf16_f32 v68, v68, v69
	v_cvt_pk_bf16_f32 v69, v74, v75
	global_store_dwordx4 v[78:79], v[66:69], off offset:256
	s_nop 1
	v_pk_mul_f32 v[66:67], v[60:61], s[0:1] op_sel_hi:[1,0]
	v_pk_mul_f32 v[60:61], v[58:59], s[0:1] op_sel_hi:[1,0]
	s_mov_b32 s1, 0x80000
	v_cvt_pk_bf16_f32 v58, v62, v63
	v_cvt_pk_bf16_f32 v59, v64, v65
	v_add_co_u32_e32 v64, vcc, s1, v122
	v_cvt_pk_bf16_f32 v60, v60, v61
	v_cvt_pk_bf16_f32 v61, v66, v67
	v_lshl_add_u64 v[62:63], v[122:123], 0, s[4:5]
	s_nop 0
	v_addc_co_u32_e32 v65, vcc, 0, v123, vcc
	global_store_dwordx4 v[64:65], v[58:61], off
	v_pk_mul_f32 v[56:57], v[56:57], s[0:1] op_sel_hi:[1,0]
	v_pk_mul_f32 v[54:55], v[54:55], s[0:1] op_sel_hi:[1,0]
	v_pk_mul_f32 v[58:59], v[48:49], s[0:1] op_sel_hi:[1,0]
	v_pk_mul_f32 v[48:49], v[46:47], s[0:1] op_sel_hi:[1,0]
	v_cvt_pk_bf16_f32 v46, v54, v55
	v_cvt_pk_bf16_f32 v47, v56, v57
	s_mov_b64 s[4:5], 0x90000
	v_cvt_pk_bf16_f32 v48, v48, v49
	v_cvt_pk_bf16_f32 v49, v58, v59
	global_store_dwordx4 v[62:63], v[46:49], off offset:256
	s_nop 1
	v_pk_mul_f32 v[46:47], v[52:53], s[0:1] op_sel_hi:[1,0]
	v_pk_mul_f32 v[48:49], v[50:51], s[0:1] op_sel_hi:[1,0]
	v_pk_mul_f32 v[50:51], v[44:45], s[0:1] op_sel_hi:[1,0]
	v_pk_mul_f32 v[44:45], v[42:43], s[0:1] op_sel_hi:[1,0]
	s_mov_b32 s1, 0x90000
	v_cvt_pk_bf16_f32 v42, v48, v49
	v_add_co_u32_e32 v48, vcc, s1, v122
	v_cvt_pk_bf16_f32 v43, v46, v47
	v_cvt_pk_bf16_f32 v44, v44, v45
	v_cvt_pk_bf16_f32 v45, v50, v51
	v_lshl_add_u64 v[46:47], v[122:123], 0, s[4:5]
	s_nop 0
	v_addc_co_u32_e32 v49, vcc, 0, v123, vcc
	global_store_dwordx4 v[48:49], v[42:45], off
	v_pk_mul_f32 v[40:41], v[40:41], s[0:1] op_sel_hi:[1,0]
	v_pk_mul_f32 v[38:39], v[38:39], s[0:1] op_sel_hi:[1,0]
	v_pk_mul_f32 v[42:43], v[32:33], s[0:1] op_sel_hi:[1,0]
	v_pk_mul_f32 v[32:33], v[30:31], s[0:1] op_sel_hi:[1,0]
	v_cvt_pk_bf16_f32 v30, v38, v39
	v_cvt_pk_bf16_f32 v31, v40, v41
	s_mov_b64 s[4:5], 0xa0000
	v_cvt_pk_bf16_f32 v32, v32, v33
	v_cvt_pk_bf16_f32 v33, v42, v43
	global_store_dwordx4 v[46:47], v[30:33], off offset:256
	s_nop 1
	v_pk_mul_f32 v[30:31], v[36:37], s[0:1] op_sel_hi:[1,0]
	v_pk_mul_f32 v[32:33], v[34:35], s[0:1] op_sel_hi:[1,0]
	v_pk_mul_f32 v[34:35], v[28:29], s[0:1] op_sel_hi:[1,0]
	v_pk_mul_f32 v[28:29], v[26:27], s[0:1] op_sel_hi:[1,0]
	s_mov_b32 s1, 0xa0000
	v_cvt_pk_bf16_f32 v26, v32, v33
	v_add_co_u32_e32 v32, vcc, s1, v122
	v_cvt_pk_bf16_f32 v27, v30, v31
	v_cvt_pk_bf16_f32 v28, v28, v29
	v_cvt_pk_bf16_f32 v29, v34, v35
	v_lshl_add_u64 v[30:31], v[122:123], 0, s[4:5]
	s_nop 0
	v_addc_co_u32_e32 v33, vcc, 0, v123, vcc
	global_store_dwordx4 v[32:33], v[26:29], off
	v_pk_mul_f32 v[24:25], v[24:25], s[0:1] op_sel_hi:[1,0]
	v_pk_mul_f32 v[22:23], v[22:23], s[0:1] op_sel_hi:[1,0]
	v_pk_mul_f32 v[26:27], v[16:17], s[0:1] op_sel_hi:[1,0]
	v_pk_mul_f32 v[16:17], v[14:15], s[0:1] op_sel_hi:[1,0]
	v_cvt_pk_bf16_f32 v14, v22, v23
	v_cvt_pk_bf16_f32 v15, v24, v25
	s_mov_b64 s[4:5], 0xb0000
	v_cvt_pk_bf16_f32 v16, v16, v17
	v_cvt_pk_bf16_f32 v17, v26, v27
	global_store_dwordx4 v[30:31], v[14:17], off offset:256
	s_nop 1
	v_pk_mul_f32 v[14:15], v[20:21], s[0:1] op_sel_hi:[1,0]
	v_pk_mul_f32 v[16:17], v[18:19], s[0:1] op_sel_hi:[1,0]
	v_pk_mul_f32 v[18:19], v[12:13], s[0:1] op_sel_hi:[1,0]
	v_pk_mul_f32 v[12:13], v[10:11], s[0:1] op_sel_hi:[1,0]
	s_mov_b32 s1, 0xb0000
	v_cvt_pk_bf16_f32 v10, v16, v17
	v_add_co_u32_e32 v16, vcc, s1, v122
	v_cvt_pk_bf16_f32 v11, v14, v15
	v_cvt_pk_bf16_f32 v12, v12, v13
	v_cvt_pk_bf16_f32 v13, v18, v19
	v_lshl_add_u64 v[14:15], v[122:123], 0, s[4:5]
	s_nop 0
	v_addc_co_u32_e32 v17, vcc, 0, v123, vcc
	global_store_dwordx4 v[16:17], v[10:13], off
	v_pk_mul_f32 v[8:9], v[8:9], s[0:1] op_sel_hi:[1,0]
	v_pk_mul_f32 v[6:7], v[6:7], s[0:1] op_sel_hi:[1,0]
	v_pk_mul_f32 v[10:11], v[4:5], s[0:1] op_sel_hi:[1,0]
	v_pk_mul_f32 v[4:5], v[2:3], s[0:1] op_sel_hi:[1,0]
	v_cvt_pk_bf16_f32 v2, v6, v7
	v_cvt_pk_bf16_f32 v3, v8, v9
	s_nop 0
	v_cvt_pk_bf16_f32 v4, v4, v5
	v_cvt_pk_bf16_f32 v5, v10, v11
	global_store_dwordx4 v[14:15], v[2:5], off offset:256
	s_waitcnt vmcnt(0)
	s_barrier
	s_cbranch_scc1 .LBB0_1596
	v_lshlrev_b32_e32 v1, 5, v162
	global_load_dwordx4 v[2:5], v1, s[80:81] offset:16 nt
	global_load_dwordx4 v[6:9], v1, s[80:81] nt
	v_mbcnt_lo_u32_b32 v1, -1, 0
	v_mbcnt_hi_u32_b32 v10, -1, v1
	v_and_b32_e32 v1, 64, v10
	v_add_u32_e32 v11, 64, v1
	v_xor_b32_e32 v1, 1, v10
	v_cmp_lt_i32_e32 vcc, v1, v11
	v_xor_b32_e32 v12, 2, v10
	s_add_u32 s20, s92, 0x21600000
	v_cndmask_b32_e32 v1, v10, v1, vcc
	v_cmp_lt_i32_e32 vcc, v12, v11
	s_addc_u32 s21, s93, 0
	s_add_u32 s22, s92, 0x27900000
	v_cndmask_b32_e32 v12, v10, v12, vcc
	v_lshlrev_b32_e32 v51, 2, v12
	v_xor_b32_e32 v12, 4, v10
	v_cmp_lt_i32_e32 vcc, v12, v11
	s_addc_u32 s23, s93, 0
	s_add_u32 s24, s92, 0x50c00000
	v_cndmask_b32_e32 v12, v10, v12, vcc
	v_lshlrev_b32_e32 v64, 2, v12
	v_xor_b32_e32 v12, 8, v10
	v_cmp_lt_i32_e32 vcc, v12, v11
	s_addc_u32 s25, s93, 0
	s_add_u32 s26, s92, 0x19200000
	v_cndmask_b32_e32 v12, v10, v12, vcc
	v_lshlrev_b32_e32 v65, 2, v12
	v_xor_b32_e32 v12, 16, v10
	v_cmp_lt_i32_e32 vcc, v12, v11
	s_addc_u32 s27, s93, 0
	v_lshlrev_b32_e32 v130, 4, v162
	v_cndmask_b32_e32 v12, v10, v12, vcc
	v_lshlrev_b32_e32 v66, 2, v12
	v_xor_b32_e32 v12, 32, v10
	v_cmp_lt_i32_e32 vcc, v12, v11
	s_add_u32 s30, s92, 0x38100000
	s_mov_b64 s[0:1], 0x2fd00000
	v_cndmask_b32_e32 v10, v10, v12, vcc
	v_lshlrev_b32_e32 v67, 2, v10
	v_lshl_add_u64 v[10:11], s[92:93], 0, v[130:131]
	s_addc_u32 s31, s93, 0
	s_lshl_b32 s34, s2, 6
	v_lshlrev_b32_e32 v50, 3, v162
	v_lshlrev_b32_e32 v1, 2, v1
	v_lshl_add_u64 v[52:53], v[10:11], 0, s[0:1]
	s_movk_i32 s35, 0x1000
	v_mov_b32_e32 v68, 0x358637bd
	s_mov_b32 s36, 0xf800000
	v_mov_b32_e32 v69, 0x260
	s_mov_b32 s37, s33
.LBB0_1595:
	s_add_i32 s0, s34, s37
	s_ashr_i32 s1, s0, 31
	s_lshr_b32 s1, s1, 19
	s_add_i32 s1, s0, s1
	s_ashr_i32 s4, s1, 13
	s_and_b32 s1, s1, 0xffffe000
	s_sub_i32 s0, s0, s1
	s_mul_hi_i32 s5, s4, 0x2100
	s_mulk_i32 s4, 0x2100
	s_ashr_i32 s1, s0, 31
	s_add_u32 s0, s4, s0
	s_addc_u32 s1, s5, s1
	s_mul_hi_u32 s4, s0, 0xc00
	s_mul_i32 s5, s0, 0xc00
	s_mul_i32 s6, s1, 0xc00
	s_lshl_b64 s[0:1], s[0:1], 13
	s_add_i32 s4, s4, s6
	v_lshl_add_u64 v[12:13], v[52:53], 0, s[0:1]
	v_or_b32_e32 v10, s5, v50
	v_mov_b32_e32 v11, s4
	v_add_co_u32_e32 v36, vcc, s35, v12
	v_lshlrev_b64 v[34:35], 1, v[10:11]
	s_nop 0
	v_addc_co_u32_e32 v37, vcc, 0, v13, vcc
	global_load_dwordx4 v[30:33], v[12:13], off nt
	global_load_dwordx4 v[26:29], v[12:13], off offset:1024 nt
	global_load_dwordx4 v[22:25], v[12:13], off offset:2048 nt
	global_load_dwordx4 v[18:21], v[12:13], off offset:3072 nt
	global_load_dwordx4 v[14:17], v[36:37], off nt
	s_nop 0
	global_load_dwordx4 v[10:13], v[36:37], off offset:1024 nt
	v_lshl_add_u64 v[36:37], s[20:21], 0, v[34:35]
	v_lshl_add_u64 v[38:39], s[22:23], 0, v[34:35]
	v_lshl_add_u64 v[40:41], s[24:25], 0, v[34:35]
	v_lshl_add_u64 v[42:43], s[26:27], 0, v[34:35]
	global_load_dwordx4 v[56:59], v[36:37], off nt
	global_load_dwordx4 v[60:63], v[36:37], off offset:2048 nt
	global_load_dwordx4 v[118:121], v[40:41], off nt
	global_load_dwordx4 v[122:125], v[40:41], off offset:2048 nt
	global_load_dwordx4 v[126:129], v[38:39], off nt
	global_load_dwordx4 v[132:135], v[36:37], off offset:3072 nt
	global_load_dwordx4 v[136:139], v[38:39], off offset:2048 nt
	global_load_dwordx4 v[140:143], v[38:39], off offset:3072 nt
	global_load_dwordx4 v[144:147], v[42:43], off nt
	global_load_dwordx4 v[148:151], v[40:41], off offset:3072 nt
	global_load_dwordx4 v[152:155], v[42:43], off offset:2048 nt
	global_load_dwordx4 v[156:159], v[42:43], off offset:3072 nt
	v_add_co_u32_e32 v36, vcc, s35, v36
	s_add_u32 s28, s30, s0
	s_nop 0
	v_addc_co_u32_e32 v37, vcc, 0, v37, vcc
	v_add_co_u32_e32 v38, vcc, s35, v38
	v_lshlrev_b32_e32 v130, 1, v50
	s_nop 0
	v_addc_co_u32_e32 v39, vcc, 0, v39, vcc
	v_add_co_u32_e32 v72, vcc, s35, v40
	s_addc_u32 s29, s31, s1
	s_nop 0
	v_addc_co_u32_e32 v73, vcc, 0, v41, vcc
	v_add_co_u32_e32 v74, vcc, s35, v42
	v_or_b32_e32 v34, 0x400, v34
	v_lshl_add_u64 v[44:45], s[28:29], 0, v[130:131]
	v_addc_co_u32_e32 v75, vcc, 0, v43, vcc
	v_lshl_add_u64 v[46:47], s[20:21], 0, v[34:35]
	v_lshl_add_u64 v[48:49], s[22:23], 0, v[34:35]
	v_lshl_add_u64 v[70:71], s[24:25], 0, v[34:35]
	v_lshl_add_u64 v[34:35], s[26:27], 0, v[34:35]
	v_add_co_u32_e32 v54, vcc, s35, v44
	s_add_i32 s0, s37, 8
	s_nop 0
	v_addc_co_u32_e32 v55, vcc, 0, v45, vcc
	global_load_dwordx4 v[164:167], v[46:47], off nt
	global_load_dwordx4 v[168:171], v[48:49], off nt
	global_load_dwordx4 v[172:175], v[70:71], off nt
	global_load_dwordx4 v[176:179], v[34:35], off nt
	global_load_dwordx4 v[180:183], v[36:37], off nt
	s_nop 0
	global_load_dwordx4 v[34:37], v[36:37], off offset:1024 nt
	s_nop 0
	global_load_dwordx4 v[184:187], v[38:39], off nt
	s_nop 0
	global_load_dwordx4 v[38:41], v[38:39], off offset:1024 nt
	s_nop 0
	global_load_dwordx4 v[188:191], v[72:73], off nt
	global_load_dwordx4 v[42:45], v[72:73], off offset:1024 nt
	global_load_dwordx4 v[192:195], v[74:75], off nt
	global_load_dwordx4 v[46:49], v[74:75], off offset:1024 nt
	s_cmp_lt_u32 s37, 56
	s_mov_b32 s37, s0
	s_waitcnt vmcnt(0)
	v_lshlrev_b32_e32 v160, 16, v62
	v_and_b32_e32 v161, 0xffff0000, v62
	v_lshlrev_b32_e32 v110, 16, v30
	v_and_b32_e32 v111, 0xffff0000, v30
	v_lshlrev_b32_e32 v78, 16, v14
	v_and_b32_e32 v79, 0xffff0000, v14
	v_lshlrev_b32_e32 v80, 16, v15
	v_and_b32_e32 v81, 0xffff0000, v15
	v_lshlrev_b32_e32 v82, 16, v16
	v_and_b32_e32 v83, 0xffff0000, v16
	v_lshlrev_b32_e32 v84, 16, v17
	v_and_b32_e32 v85, 0xffff0000, v17
	v_lshlrev_b32_e32 v70, 16, v10
	v_and_b32_e32 v71, 0xffff0000, v10
	v_lshlrev_b32_e32 v72, 16, v11
	v_and_b32_e32 v73, 0xffff0000, v11
	v_lshlrev_b32_e32 v74, 16, v12
	v_and_b32_e32 v75, 0xffff0000, v12
	v_lshlrev_b32_e32 v76, 16, v13
	v_and_b32_e32 v77, 0xffff0000, v13
	v_lshlrev_b32_e32 v10, 16, v56
	v_and_b32_e32 v11, 0xffff0000, v56
	v_lshlrev_b32_e32 v12, 16, v126
	v_and_b32_e32 v13, 0xffff0000, v126
	v_lshlrev_b32_e32 v14, 16, v118
	v_and_b32_e32 v15, 0xffff0000, v118
	v_lshlrev_b32_e32 v16, 16, v144
	v_and_b32_e32 v17, 0xffff0000, v144
	v_lshlrev_b32_e32 v112, 16, v31
	v_and_b32_e32 v113, 0xffff0000, v31
	v_lshlrev_b32_e32 v114, 16, v32
	v_and_b32_e32 v115, 0xffff0000, v32
	v_lshlrev_b32_e32 v116, 16, v33
	v_and_b32_e32 v117, 0xffff0000, v33
	v_lshlrev_b32_e32 v102, 16, v26
	v_and_b32_e32 v103, 0xffff0000, v26
	v_lshlrev_b32_e32 v104, 16, v27
	v_and_b32_e32 v105, 0xffff0000, v27
	v_lshlrev_b32_e32 v106, 16, v28
	v_and_b32_e32 v107, 0xffff0000, v28
	v_lshlrev_b32_e32 v108, 16, v29
	v_and_b32_e32 v109, 0xffff0000, v29
	v_lshlrev_b32_e32 v94, 16, v22
	v_and_b32_e32 v95, 0xffff0000, v22
	v_lshlrev_b32_e32 v96, 16, v23
	v_and_b32_e32 v97, 0xffff0000, v23
	v_lshlrev_b32_e32 v98, 16, v24
	v_and_b32_e32 v99, 0xffff0000, v24
	v_lshlrev_b32_e32 v100, 16, v25
	v_and_b32_e32 v101, 0xffff0000, v25
	v_lshlrev_b32_e32 v86, 16, v18
	v_and_b32_e32 v87, 0xffff0000, v18
	v_lshlrev_b32_e32 v88, 16, v19
	v_and_b32_e32 v89, 0xffff0000, v19
	v_lshlrev_b32_e32 v90, 16, v20
	v_and_b32_e32 v91, 0xffff0000, v20
	v_lshlrev_b32_e32 v92, 16, v21
	v_and_b32_e32 v93, 0xffff0000, v21
	v_lshlrev_b32_e32 v18, 16, v57
	v_and_b32_e32 v19, 0xffff0000, v57
	v_lshlrev_b32_e32 v20, 16, v127
	v_and_b32_e32 v21, 0xffff0000, v127
	v_lshlrev_b32_e32 v22, 16, v119
	v_and_b32_e32 v23, 0xffff0000, v119
	v_lshlrev_b32_e32 v24, 16, v145
	v_and_b32_e32 v25, 0xffff0000, v145
	v_lshlrev_b32_e32 v26, 16, v58
	v_and_b32_e32 v27, 0xffff0000, v58
	v_lshlrev_b32_e32 v28, 16, v128
	v_and_b32_e32 v29, 0xffff0000, v128
	v_lshlrev_b32_e32 v30, 16, v120
	v_and_b32_e32 v31, 0xffff0000, v120
	v_lshlrev_b32_e32 v32, 16, v146
	v_and_b32_e32 v33, 0xffff0000, v146
	v_lshlrev_b32_e32 v56, 16, v59
	v_and_b32_e32 v57, 0xffff0000, v59
	v_lshlrev_b32_e32 v58, 16, v129
	v_and_b32_e32 v59, 0xffff0000, v129
	v_lshlrev_b32_e32 v118, 16, v121
	v_and_b32_e32 v119, 0xffff0000, v121
	v_lshlrev_b32_e32 v120, 16, v147
	v_and_b32_e32 v121, 0xffff0000, v147
	v_lshlrev_b32_e32 v126, 16, v60
	v_and_b32_e32 v127, 0xffff0000, v60
	v_lshlrev_b32_e32 v128, 16, v136
	v_and_b32_e32 v129, 0xffff0000, v136
	v_lshlrev_b32_e32 v144, 16, v122
	v_and_b32_e32 v145, 0xffff0000, v122
	v_lshlrev_b32_e32 v146, 16, v152
	v_and_b32_e32 v147, 0xffff0000, v152
	v_lshlrev_b32_e32 v60, 16, v61
	v_and_b32_e32 v61, 0xffff0000, v61
	v_lshlrev_b32_e32 v136, 16, v137
	v_and_b32_e32 v137, 0xffff0000, v137
	v_lshlrev_b32_e32 v122, 16, v123
	v_and_b32_e32 v123, 0xffff0000, v123
	v_lshlrev_b32_e32 v152, 16, v153
	v_and_b32_e32 v153, 0xffff0000, v153
	v_lshlrev_b32_e32 v196, 16, v138
	v_and_b32_e32 v197, 0xffff0000, v138
	v_lshlrev_b32_e32 v198, 16, v124
	v_and_b32_e32 v199, 0xffff0000, v124
	v_lshlrev_b32_e32 v200, 16, v154
	v_and_b32_e32 v201, 0xffff0000, v154
	v_lshlrev_b32_e32 v62, 16, v63
	v_and_b32_e32 v63, 0xffff0000, v63
	v_lshlrev_b32_e32 v138, 16, v139
	v_and_b32_e32 v139, 0xffff0000, v139
	v_lshlrev_b32_e32 v124, 16, v125
	v_and_b32_e32 v125, 0xffff0000, v125
	v_lshlrev_b32_e32 v154, 16, v155
	v_and_b32_e32 v155, 0xffff0000, v155
	v_lshlrev_b32_e32 v202, 16, v132
	v_and_b32_e32 v203, 0xffff0000, v132
	v_lshlrev_b32_e32 v204, 16, v140
	v_and_b32_e32 v205, 0xffff0000, v140
	v_lshlrev_b32_e32 v206, 16, v148
	v_and_b32_e32 v207, 0xffff0000, v148
	v_lshlrev_b32_e32 v208, 16, v156
	v_and_b32_e32 v209, 0xffff0000, v156
	v_lshlrev_b32_e32 v132, 16, v133
	v_and_b32_e32 v133, 0xffff0000, v133
	v_lshlrev_b32_e32 v140, 16, v141
	v_and_b32_e32 v141, 0xffff0000, v141
	v_lshlrev_b32_e32 v148, 16, v149
	v_and_b32_e32 v149, 0xffff0000, v149
	v_lshlrev_b32_e32 v156, 16, v157
	v_and_b32_e32 v157, 0xffff0000, v157
	v_lshlrev_b32_e32 v210, 16, v134
	v_and_b32_e32 v211, 0xffff0000, v134
	v_lshlrev_b32_e32 v212, 16, v142
	v_and_b32_e32 v213, 0xffff0000, v142
	v_lshlrev_b32_e32 v214, 16, v150
	v_and_b32_e32 v215, 0xffff0000, v150
	v_lshlrev_b32_e32 v216, 16, v158
	v_and_b32_e32 v217, 0xffff0000, v158
	v_lshlrev_b32_e32 v134, 16, v135
	v_and_b32_e32 v135, 0xffff0000, v135
	v_lshlrev_b32_e32 v142, 16, v143
	v_and_b32_e32 v143, 0xffff0000, v143
	v_lshlrev_b32_e32 v150, 16, v151
	v_and_b32_e32 v151, 0xffff0000, v151
	v_lshlrev_b32_e32 v158, 16, v159
	v_and_b32_e32 v159, 0xffff0000, v159
	v_pk_add_f32 v[10:11], v[10:11], v[12:13]
	v_pk_add_f32 v[12:13], v[14:15], v[16:17]
	v_pk_add_f32 v[14:15], v[18:19], v[20:21]
	v_pk_add_f32 v[16:17], v[22:23], v[24:25]
	v_pk_add_f32 v[18:19], v[26:27], v[28:29]
	v_pk_add_f32 v[20:21], v[30:31], v[32:33]
	v_pk_add_f32 v[22:23], v[56:57], v[58:59]
	v_pk_add_f32 v[24:25], v[118:119], v[120:121]
	v_lshlrev_b32_e32 v26, 16, v164
	v_and_b32_e32 v27, 0xffff0000, v164
	v_lshlrev_b32_e32 v28, 16, v168
	v_and_b32_e32 v29, 0xffff0000, v168
	v_lshlrev_b32_e32 v30, 16, v172
	v_and_b32_e32 v31, 0xffff0000, v172
	v_lshlrev_b32_e32 v32, 16, v176
	v_and_b32_e32 v33, 0xffff0000, v176
	v_lshlrev_b32_e32 v56, 16, v165
	v_and_b32_e32 v57, 0xffff0000, v165
	v_lshlrev_b32_e32 v58, 16, v169
	v_and_b32_e32 v59, 0xffff0000, v169
	v_lshlrev_b32_e32 v118, 16, v173
	v_and_b32_e32 v119, 0xffff0000, v173
	v_lshlrev_b32_e32 v120, 16, v177
	v_and_b32_e32 v121, 0xffff0000, v177
	v_lshlrev_b32_e32 v164, 16, v166
	v_and_b32_e32 v165, 0xffff0000, v166
	v_lshlrev_b32_e32 v168, 16, v170
	v_and_b32_e32 v169, 0xffff0000, v170
	v_lshlrev_b32_e32 v172, 16, v174
	v_and_b32_e32 v173, 0xffff0000, v174
	v_lshlrev_b32_e32 v176, 16, v178
	v_and_b32_e32 v177, 0xffff0000, v178
	v_pk_add_f32 v[126:127], v[126:127], v[128:129]
	v_pk_add_f32 v[128:129], v[144:145], v[146:147]
	v_pk_add_f32 v[60:61], v[60:61], v[136:137]
	v_pk_add_f32 v[122:123], v[122:123], v[152:153]
	v_pk_add_f32 v[136:137], v[160:161], v[196:197]
	v_pk_add_f32 v[144:145], v[198:199], v[200:201]
	v_pk_add_f32 v[62:63], v[62:63], v[138:139]
	v_pk_add_f32 v[124:125], v[124:125], v[154:155]
	v_pk_add_f32 v[138:139], v[202:203], v[204:205]
	v_pk_add_f32 v[146:147], v[206:207], v[208:209]
	v_pk_add_f32 v[132:133], v[132:133], v[140:141]
	v_pk_add_f32 v[140:141], v[148:149], v[156:157]
	v_pk_add_f32 v[148:149], v[210:211], v[212:213]
	v_pk_add_f32 v[152:153], v[214:215], v[216:217]
	v_pk_add_f32 v[134:135], v[134:135], v[142:143]
	v_pk_add_f32 v[142:143], v[150:151], v[158:159]
	v_lshlrev_b32_e32 v150, 16, v180
	v_and_b32_e32 v151, 0xffff0000, v180
	v_lshlrev_b32_e32 v154, 16, v184
	v_and_b32_e32 v155, 0xffff0000, v184
	v_lshlrev_b32_e32 v156, 16, v188
	v_and_b32_e32 v157, 0xffff0000, v188
	v_lshlrev_b32_e32 v158, 16, v192
	v_and_b32_e32 v159, 0xffff0000, v192
	v_lshlrev_b32_e32 v202, 16, v34
	v_and_b32_e32 v203, 0xffff0000, v34
	v_lshlrev_b32_e32 v204, 16, v38
	v_and_b32_e32 v205, 0xffff0000, v38
	v_lshlrev_b32_e32 v206, 16, v42
	v_and_b32_e32 v207, 0xffff0000, v42
	v_lshlrev_b32_e32 v208, 16, v46
	v_and_b32_e32 v209, 0xffff0000, v46
	v_lshlrev_b32_e32 v214, 16, v43
	v_and_b32_e32 v215, 0xffff0000, v43
	v_lshlrev_b32_e32 v218, 16, v36
	v_and_b32_e32 v219, 0xffff0000, v36
	v_lshlrev_b32_e32 v220, 16, v40
	v_and_b32_e32 v221, 0xffff0000, v40
	v_lshlrev_b32_e32 v222, 16, v44
	v_and_b32_e32 v223, 0xffff0000, v44
	v_lshlrev_b32_e32 v224, 16, v48
	v_and_b32_e32 v225, 0xffff0000, v48
	v_pk_add_f32 v[42:43], v[10:11], v[12:13]
	v_lshlrev_b32_e32 v166, 16, v167
	v_and_b32_e32 v167, 0xffff0000, v167
	v_lshlrev_b32_e32 v170, 16, v171
	v_and_b32_e32 v171, 0xffff0000, v171
	v_lshlrev_b32_e32 v174, 16, v175
	v_and_b32_e32 v175, 0xffff0000, v175
	v_lshlrev_b32_e32 v178, 16, v179
	v_and_b32_e32 v179, 0xffff0000, v179
	v_lshlrev_b32_e32 v160, 16, v181
	v_and_b32_e32 v161, 0xffff0000, v181
	v_lshlrev_b32_e32 v180, 16, v185
	v_and_b32_e32 v181, 0xffff0000, v185
	v_lshlrev_b32_e32 v184, 16, v189
	v_and_b32_e32 v185, 0xffff0000, v189
	v_lshlrev_b32_e32 v188, 16, v193
	v_and_b32_e32 v189, 0xffff0000, v193
	v_lshlrev_b32_e32 v192, 16, v182
	v_and_b32_e32 v193, 0xffff0000, v182
	v_lshlrev_b32_e32 v196, 16, v186
	v_and_b32_e32 v197, 0xffff0000, v186
	v_lshlrev_b32_e32 v198, 16, v190
	v_and_b32_e32 v199, 0xffff0000, v190
	v_lshlrev_b32_e32 v200, 16, v194
	v_and_b32_e32 v201, 0xffff0000, v194
	v_lshlrev_b32_e32 v210, 16, v35
	v_and_b32_e32 v211, 0xffff0000, v35
	v_lshlrev_b32_e32 v212, 16, v39
	v_and_b32_e32 v213, 0xffff0000, v39
	v_lshlrev_b32_e32 v216, 16, v47
	v_and_b32_e32 v217, 0xffff0000, v47
	v_lshlrev_b32_e32 v230, 16, v45
	v_and_b32_e32 v231, 0xffff0000, v45
	v_lshlrev_b32_e32 v232, 16, v49
	v_and_b32_e32 v233, 0xffff0000, v49
	v_pk_add_f32 v[44:45], v[14:15], v[16:17]
	v_pk_add_f32 v[46:47], v[18:19], v[20:21]
	v_pk_add_f32 v[48:49], v[22:23], v[24:25]
	v_pk_add_f32 v[10:11], v[26:27], v[28:29]
	v_pk_add_f32 v[12:13], v[30:31], v[32:33]
	v_pk_add_f32 v[14:15], v[56:57], v[58:59]
	v_pk_add_f32 v[16:17], v[118:119], v[120:121]
	v_pk_add_f32 v[26:27], v[164:165], v[168:169]
	v_pk_add_f32 v[28:29], v[172:173], v[176:177]
	v_pk_add_f32 v[34:35], v[126:127], v[128:129]
	v_pk_add_f32 v[38:39], v[136:137], v[144:145]
	v_pk_add_f32 v[18:19], v[138:139], v[146:147]
	v_pk_add_f32 v[22:23], v[148:149], v[152:153]
	v_pk_add_f32 v[118:119], v[150:151], v[154:155]
	v_pk_add_f32 v[120:121], v[156:157], v[158:159]
	v_pk_add_f32 v[136:137], v[202:203], v[204:205]
	v_pk_add_f32 v[138:139], v[206:207], v[208:209]
	v_pk_add_f32 v[144:145], v[218:219], v[220:221]
	v_pk_add_f32 v[146:147], v[222:223], v[224:225]
	v_pk_mul_f32 v[152:153], v[42:43], v[42:43]
	v_lshlrev_b32_e32 v226, 16, v37
	v_and_b32_e32 v227, 0xffff0000, v37
	v_lshlrev_b32_e32 v228, 16, v41
	v_and_b32_e32 v229, 0xffff0000, v41
	v_pk_add_f32 v[30:31], v[166:167], v[170:171]
	v_pk_add_f32 v[32:33], v[174:175], v[178:179]
	v_pk_add_f32 v[36:37], v[60:61], v[122:123]
	v_pk_add_f32 v[40:41], v[62:63], v[124:125]
	v_pk_add_f32 v[20:21], v[132:133], v[140:141]
	v_pk_add_f32 v[24:25], v[134:135], v[142:143]
	v_pk_add_f32 v[122:123], v[160:161], v[180:181]
	v_pk_add_f32 v[124:125], v[184:185], v[188:189]
	v_pk_add_f32 v[126:127], v[192:193], v[196:197]
	v_pk_add_f32 v[128:129], v[198:199], v[200:201]
	v_pk_add_f32 v[140:141], v[210:211], v[212:213]
	v_pk_add_f32 v[142:143], v[214:215], v[216:217]
	v_pk_mul_f32 v[154:155], v[44:45], v[44:45]
	v_pk_add_f32 v[56:57], v[10:11], v[12:13]
	v_pk_add_f32 v[58:59], v[14:15], v[16:17]
	v_pk_add_f32 v[60:61], v[26:27], v[28:29]
	v_pk_mul_f32 v[160:161], v[34:35], v[34:35]
	v_pk_mul_f32 v[170:171], v[18:19], v[18:19]
	v_pk_add_f32 v[26:27], v[118:119], v[120:121]
	v_pk_add_f32 v[10:11], v[136:137], v[138:139]
	v_pk_add_f32 v[14:15], v[144:145], v[146:147]
	v_add_f32_e32 v144, v152, v153
	v_pk_add_f32 v[62:63], v[30:31], v[32:33]
	v_pk_mul_f32 v[164:165], v[36:37], v[36:37]
	v_pk_mul_f32 v[172:173], v[20:21], v[20:21]
	v_pk_add_f32 v[28:29], v[122:123], v[124:125]
	v_pk_add_f32 v[30:31], v[126:127], v[128:129]
	v_pk_add_f32 v[12:13], v[140:141], v[142:143]
	v_pk_mul_f32 v[118:119], v[56:57], v[56:57]
	v_add_f32_e32 v145, v160, v161
	v_add_f32_e32 v146, v170, v171
	v_pk_mul_f32 v[126:127], v[26:27], v[26:27]
	v_pk_mul_f32 v[136:137], v[10:11], v[10:11]
	v_add_f32_e32 v144, v154, v144
	v_pk_mul_f32 v[156:157], v[46:47], v[46:47]
	v_pk_mul_f32 v[120:121], v[58:59], v[58:59]
	v_pk_mul_f32 v[128:129], v[28:29], v[28:29]
	v_pk_mul_f32 v[138:139], v[12:13], v[12:13]
	v_add_f32_e32 v118, v118, v119
	v_add_f32_e32 v119, v164, v145
	v_add_f32_e32 v145, v172, v146
	v_add_f32_e32 v126, v126, v127
	v_add_f32_e32 v127, v136, v137
	v_add_f32_e32 v136, v155, v144
	v_lshlrev_b32_e32 v182, 16, v183
	v_and_b32_e32 v183, 0xffff0000, v183
	v_lshlrev_b32_e32 v186, 16, v187
	v_and_b32_e32 v187, 0xffff0000, v187
	v_lshlrev_b32_e32 v190, 16, v191
	v_and_b32_e32 v191, 0xffff0000, v191
	v_lshlrev_b32_e32 v194, 16, v195
	v_and_b32_e32 v195, 0xffff0000, v195
	v_pk_mul_f32 v[166:167], v[38:39], v[38:39]
	v_pk_mul_f32 v[174:175], v[22:23], v[22:23]
	v_add_f32_e32 v118, v120, v118
	v_add_f32_e32 v119, v165, v119
	v_add_f32_e32 v120, v173, v145
	v_add_f32_e32 v126, v128, v126
	v_add_f32_e32 v127, v138, v127
	v_add_f32_e32 v128, v156, v136
	v_pk_add_f32 v[132:133], v[182:183], v[186:187]
	v_pk_add_f32 v[134:135], v[190:191], v[194:195]
	v_pk_mul_f32 v[158:159], v[48:49], v[48:49]
	v_pk_mul_f32 v[122:123], v[60:61], v[60:61]
	v_pk_mul_f32 v[140:141], v[14:15], v[14:15]
	v_add_f32_e32 v118, v121, v118
	v_add_f32_e32 v119, v166, v119
	v_add_f32_e32 v120, v174, v120
	v_add_f32_e32 v121, v129, v126
	v_add_f32_e32 v126, v139, v127
	v_add_f32_e32 v127, v157, v128
	v_pk_add_f32 v[148:149], v[226:227], v[228:229]
	v_pk_add_f32 v[150:151], v[230:231], v[232:233]
	v_pk_mul_f32 v[168:169], v[40:41], v[40:41]
	v_pk_mul_f32 v[176:177], v[24:25], v[24:25]
	v_pk_add_f32 v[32:33], v[132:133], v[134:135]
	v_pk_mul_f32 v[132:133], v[30:31], v[30:31]
	v_add_f32_e32 v118, v122, v118
	v_add_f32_e32 v119, v167, v119
	v_add_f32_e32 v120, v175, v120
	v_add_f32_e32 v122, v140, v126
	v_add_f32_e32 v126, v158, v127
	v_pk_add_f32 v[16:17], v[148:149], v[150:151]
	v_pk_mul_f32 v[124:125], v[62:63], v[62:63]
	v_add_f32_e32 v121, v132, v121
	v_add_f32_e32 v118, v123, v118
	v_add_f32_e32 v119, v168, v119
	v_add_f32_e32 v120, v176, v120
	v_add_f32_e32 v123, v159, v126
	v_pk_mul_f32 v[134:135], v[32:33], v[32:33]
	v_pk_mul_f32 v[142:143], v[16:17], v[16:17]
	v_add_f32_e32 v121, v133, v121
	v_add_f32_e32 v122, v141, v122
	v_add_f32_e32 v118, v124, v118
	v_add_f32_e32 v119, v169, v119
	v_add_f32_e32 v120, v177, v120
	ds_bpermute_b32 v124, v1, v123
	v_add_f32_e32 v121, v134, v121
	v_add_f32_e32 v122, v142, v122
	v_add_f32_e32 v118, v125, v118
	ds_bpermute_b32 v125, v1, v119
	ds_bpermute_b32 v126, v1, v120
	v_add_f32_e32 v121, v135, v121
	v_add_f32_e32 v122, v143, v122
	ds_bpermute_b32 v127, v1, v118
	ds_bpermute_b32 v128, v1, v121
	ds_bpermute_b32 v129, v1, v122
	s_waitcnt lgkmcnt(5)
	v_add_f32_e32 v123, v123, v124
	s_waitcnt lgkmcnt(4)
	v_add_f32_e32 v119, v119, v125
	s_waitcnt lgkmcnt(3)
	v_add_f32_e32 v120, v120, v126
	ds_bpermute_b32 v124, v51, v123
	s_waitcnt lgkmcnt(3)
	v_add_f32_e32 v118, v118, v127
	ds_bpermute_b32 v125, v51, v119
	ds_bpermute_b32 v126, v51, v120
	s_waitcnt lgkmcnt(4)
	v_add_f32_e32 v121, v121, v128
	s_waitcnt lgkmcnt(3)
	v_add_f32_e32 v122, v122, v129
	ds_bpermute_b32 v127, v51, v118
	ds_bpermute_b32 v128, v51, v121
	ds_bpermute_b32 v129, v51, v122
	s_waitcnt lgkmcnt(5)
	v_add_f32_e32 v123, v123, v124
	s_waitcnt lgkmcnt(4)
	v_add_f32_e32 v119, v119, v125
	s_waitcnt lgkmcnt(3)
	v_add_f32_e32 v120, v120, v126
	ds_bpermute_b32 v124, v64, v123
	s_waitcnt lgkmcnt(3)
	v_add_f32_e32 v118, v118, v127
	ds_bpermute_b32 v125, v64, v119
	ds_bpermute_b32 v126, v64, v120
	s_waitcnt lgkmcnt(4)
	v_add_f32_e32 v121, v121, v128
	s_waitcnt lgkmcnt(3)
	v_add_f32_e32 v122, v122, v129
	ds_bpermute_b32 v127, v64, v118
	ds_bpermute_b32 v128, v64, v121
	ds_bpermute_b32 v129, v64, v122
	s_waitcnt lgkmcnt(5)
	v_add_f32_e32 v123, v123, v124
	s_waitcnt lgkmcnt(4)
	v_add_f32_e32 v119, v119, v125
	s_waitcnt lgkmcnt(3)
	v_add_f32_e32 v120, v120, v126
	ds_bpermute_b32 v124, v65, v123
	s_waitcnt lgkmcnt(3)
	v_add_f32_e32 v118, v118, v127
	ds_bpermute_b32 v125, v65, v119
	ds_bpermute_b32 v126, v65, v120
	s_waitcnt lgkmcnt(4)
	v_add_f32_e32 v121, v121, v128
	s_waitcnt lgkmcnt(3)
	v_add_f32_e32 v122, v122, v129
	ds_bpermute_b32 v127, v65, v118
	ds_bpermute_b32 v128, v65, v121
	ds_bpermute_b32 v129, v65, v122
	s_waitcnt lgkmcnt(5)
	v_add_f32_e32 v123, v123, v124
	s_waitcnt lgkmcnt(4)
	v_add_f32_e32 v119, v119, v125
	s_waitcnt lgkmcnt(3)
	v_add_f32_e32 v120, v120, v126
	ds_bpermute_b32 v124, v66, v123
	s_waitcnt lgkmcnt(3)
	v_add_f32_e32 v118, v118, v127
	ds_bpermute_b32 v125, v66, v119
	ds_bpermute_b32 v126, v66, v120
	s_waitcnt lgkmcnt(4)
	v_add_f32_e32 v121, v121, v128
	s_waitcnt lgkmcnt(3)
	v_add_f32_e32 v122, v122, v129
	ds_bpermute_b32 v127, v66, v118
	ds_bpermute_b32 v128, v66, v121
	ds_bpermute_b32 v129, v66, v122
	s_waitcnt lgkmcnt(5)
	v_add_f32_e32 v123, v123, v124
	s_waitcnt lgkmcnt(4)
	v_add_f32_e32 v119, v119, v125
	s_waitcnt lgkmcnt(3)
	v_add_f32_e32 v120, v120, v126
	ds_bpermute_b32 v124, v67, v123
	s_waitcnt lgkmcnt(3)
	v_add_f32_e32 v118, v118, v127
	ds_bpermute_b32 v125, v67, v119
	ds_bpermute_b32 v126, v67, v120
	s_waitcnt lgkmcnt(4)
	v_add_f32_e32 v121, v121, v128
	s_waitcnt lgkmcnt(3)
	v_add_f32_e32 v122, v122, v129
	ds_bpermute_b32 v127, v67, v118
	ds_bpermute_b32 v128, v67, v121
	ds_bpermute_b32 v129, v67, v122
	s_waitcnt lgkmcnt(5)
	v_add_f32_e32 v123, v123, v124
	s_waitcnt lgkmcnt(4)
	v_add_f32_e32 v119, v119, v125
	s_waitcnt lgkmcnt(3)
	v_add_f32_e32 v120, v120, v126
	v_fmamk_f32 v123, v123, 0x3b000000, v68
	s_waitcnt lgkmcnt(2)
	v_add_f32_e32 v118, v118, v127
	v_fmamk_f32 v119, v119, 0x3b000000, v68
	v_fmamk_f32 v120, v120, 0x3b000000, v68
	v_mul_f32_e32 v124, 0x4f800000, v123
	v_cmp_gt_f32_e64 s[4:5], s36, v123
	s_waitcnt lgkmcnt(1)
	v_add_f32_e32 v121, v121, v128
	s_waitcnt lgkmcnt(0)
	v_add_f32_e32 v122, v122, v129
	v_fmamk_f32 v118, v118, 0x3b000000, v68
	v_mul_f32_e32 v125, 0x4f800000, v119
	v_cmp_gt_f32_e32 vcc, s36, v119
	v_mul_f32_e32 v126, 0x4f800000, v120
	v_cmp_gt_f32_e64 s[0:1], s36, v120
	v_cndmask_b32_e64 v123, v123, v124, s[4:5]
	v_fmamk_f32 v121, v121, 0x3b000000, v68
	v_fmamk_f32 v122, v122, 0x3b000000, v68
	v_mul_f32_e32 v124, 0x4f800000, v118
	v_cmp_gt_f32_e64 s[6:7], s36, v118
	v_cndmask_b32_e32 v119, v119, v125, vcc
	v_cndmask_b32_e64 v120, v120, v126, s[0:1]
	v_sqrt_f32_e32 v127, v123
	v_mul_f32_e32 v125, 0x4f800000, v121
	v_cmp_gt_f32_e64 s[8:9], s36, v121
	v_mul_f32_e32 v126, 0x4f800000, v122
	v_cmp_gt_f32_e64 s[10:11], s36, v122
	v_cndmask_b32_e64 v118, v118, v124, s[6:7]
	v_sqrt_f32_e32 v124, v119
	v_sqrt_f32_e32 v128, v120
	v_cndmask_b32_e64 v121, v121, v125, s[8:9]
	v_cndmask_b32_e64 v122, v122, v126, s[10:11]
	v_sqrt_f32_e32 v125, v118
	v_sqrt_f32_e32 v126, v121
	v_sqrt_f32_e32 v129, v122
	v_add_u32_e32 v132, -1, v127
	v_add_u32_e32 v133, 1, v127
	v_add_u32_e32 v134, -1, v124
	v_add_u32_e32 v136, -1, v128
	v_fma_f32 v138, -v132, v127, v123
	v_add_u32_e32 v135, 1, v124
	v_add_u32_e32 v137, 1, v128
	v_fma_f32 v139, -v133, v127, v123
	v_add_u32_e32 v140, -1, v125
	v_fma_f32 v142, -v134, v124, v119
	v_fma_f32 v144, -v136, v128, v120
	v_cmp_ge_f32_e64 s[12:13], 0, v138
	v_add_u32_e32 v141, 1, v125
	v_fma_f32 v143, -v135, v124, v119
	v_fma_f32 v145, -v137, v128, v120
	v_add_u32_e32 v146, -1, v126
	v_add_u32_e32 v148, -1, v129
	v_cndmask_b32_e64 v127, v127, v132, s[12:13]
	v_fma_f32 v132, -v140, v125, v118
	v_cmp_ge_f32_e64 s[12:13], 0, v142
	v_cmp_ge_f32_e64 s[14:15], 0, v144
	v_cmp_lt_f32_e64 s[16:17], 0, v139
	v_add_u32_e32 v147, 1, v126
	v_add_u32_e32 v149, 1, v129
	v_fma_f32 v138, -v141, v125, v118
	v_cndmask_b32_e64 v124, v124, v134, s[12:13]
	v_cmp_lt_f32_e64 s[12:13], 0, v143
	v_cndmask_b32_e64 v128, v128, v136, s[14:15]
	v_cmp_lt_f32_e64 s[14:15], 0, v145
	v_fma_f32 v134, -v146, v126, v121
	v_fma_f32 v142, -v148, v129, v122
	v_cndmask_b32_e64 v127, v127, v133, s[16:17]
	v_cmp_ge_f32_e64 s[16:17], 0, v132
	v_fma_f32 v136, -v147, v126, v121
	v_fma_f32 v143, -v149, v129, v122
	v_cndmask_b32_e64 v125, v125, v140, s[16:17]
	v_cmp_lt_f32_e64 s[16:17], 0, v138
	v_cndmask_b32_e64 v124, v124, v135, s[12:13]
	v_cndmask_b32_e64 v128, v128, v137, s[14:15]
	v_cmp_ge_f32_e64 s[12:13], 0, v134
	v_cmp_ge_f32_e64 s[14:15], 0, v142
	v_mul_f32_e32 v132, 0x37800000, v127
	v_cndmask_b32_e64 v126, v126, v146, s[12:13]
	v_cmp_lt_f32_e64 s[12:13], 0, v136
	v_cndmask_b32_e64 v129, v129, v148, s[14:15]
	v_cmp_lt_f32_e64 s[14:15], 0, v143
	v_cndmask_b32_e64 v125, v125, v141, s[16:17]
	v_mul_f32_e32 v133, 0x37800000, v124
	v_mul_f32_e32 v134, 0x37800000, v128
	v_cndmask_b32_e64 v126, v126, v147, s[12:13]
	v_cndmask_b32_e64 v129, v129, v149, s[14:15]
	v_cndmask_b32_e64 v127, v127, v132, s[4:5]
	v_mul_f32_e32 v132, 0x37800000, v125
	v_cmp_class_f32_e64 s[4:5], v123, v69
	v_cndmask_b32_e32 v124, v124, v133, vcc
	v_cmp_class_f32_e32 vcc, v119, v69
	v_cndmask_b32_e64 v128, v128, v134, s[0:1]
	v_cmp_class_f32_e64 s[0:1], v120, v69
	v_mul_f32_e32 v133, 0x37800000, v126
	v_mul_f32_e32 v134, 0x37800000, v129
	v_cndmask_b32_e64 v123, v127, v123, s[4:5]
	v_cndmask_b32_e64 v125, v125, v132, s[6:7]
	v_cmp_class_f32_e64 s[4:5], v118, v69
	v_cndmask_b32_e32 v119, v124, v119, vcc
	v_cndmask_b32_e64 v120, v128, v120, s[0:1]
	v_cndmask_b32_e64 v124, v126, v133, s[8:9]
	v_cmp_class_f32_e32 vcc, v121, v69
	v_cndmask_b32_e64 v126, v129, v134, s[10:11]
	v_cmp_class_f32_e64 s[0:1], v122, v69
	v_div_scale_f32 v127, s[6:7], v123, v123, 1.0
	v_cndmask_b32_e64 v125, v125, v118, s[4:5]
	v_div_scale_f32 v118, s[4:5], v119, v119, 1.0
	v_div_scale_f32 v132, s[8:9], v120, v120, 1.0
	v_cndmask_b32_e32 v121, v124, v121, vcc
	v_cndmask_b32_e64 v122, v126, v122, s[0:1]
	v_rcp_f32_e32 v124, v127
	v_div_scale_f32 v126, s[0:1], v125, v125, 1.0
	v_rcp_f32_e32 v135, v118
	v_rcp_f32_e32 v136, v132
	v_div_scale_f32 v137, s[0:1], v121, v121, 1.0
	v_div_scale_f32 v139, s[0:1], v122, v122, 1.0
	v_rcp_f32_e32 v141, v126
	v_rcp_f32_e32 v142, v137
	v_rcp_f32_e32 v143, v139
	v_fma_f32 v144, -v127, v124, 1.0
	v_div_scale_f32 v128, s[6:7], 1.0, v123, 1.0
	v_fma_f32 v145, -v118, v135, 1.0
	v_fma_f32 v146, -v132, v136, 1.0
	v_fmac_f32_e32 v124, v144, v124
	v_fma_f32 v144, -v126, v141, 1.0
	v_div_scale_f32 v129, s[4:5], 1.0, v119, 1.0
	v_div_scale_f32 v134, s[10:11], 1.0, v125, 1.0
	v_fmac_f32_e32 v135, v145, v135
	v_fmac_f32_e32 v136, v146, v136
	v_fma_f32 v145, -v137, v142, 1.0
	v_fma_f32 v146, -v139, v143, 1.0
	v_mul_f32_e32 v147, v128, v124
	v_fmac_f32_e32 v141, v144, v141
	v_mul_f32_e32 v144, v129, v135
	v_fmac_f32_e32 v142, v145, v142
	v_fmac_f32_e32 v143, v146, v143
	v_fma_f32 v145, -v127, v147, v128
	v_mul_f32_e32 v146, v134, v141
	v_div_scale_f32 v133, s[8:9], 1.0, v120, 1.0
	v_fma_f32 v149, -v118, v144, v129
	v_fmac_f32_e32 v147, v145, v124
	v_fma_f32 v145, -v126, v146, v134
	v_div_scale_f32 v138, s[12:13], 1.0, v121, 1.0
	v_mul_f32_e32 v148, v133, v136
	v_fmac_f32_e32 v144, v149, v135
	v_fma_f32 v127, -v127, v147, v128
	v_fmac_f32_e32 v146, v145, v141
	s_mov_b64 vcc, s[6:7]
	v_fma_f32 v150, -v132, v148, v133
	v_mul_f32_e32 v151, v138, v142
	v_fma_f32 v128, -v118, v144, v129
	v_div_fmas_f32 v118, v127, v124, v147
	v_fma_f32 v124, -v126, v146, v134
	s_mov_b64 vcc, s[10:11]
	v_div_scale_f32 v140, s[0:1], 1.0, v122, 1.0
	v_fmac_f32_e32 v148, v150, v136
	v_fma_f32 v149, -v137, v151, v138
	v_div_fixup_f32 v118, v118, v123, 1.0
	v_div_fmas_f32 v123, v124, v141, v146
	s_mov_b64 vcc, s[4:5]
	v_mul_f32_e32 v152, v140, v143
	v_fma_f32 v129, -v132, v148, v133
	v_fmac_f32_e32 v151, v149, v142
	v_pk_mul_f32 v[42:43], v[42:43], v[118:119] op_sel_hi:[1,0]
	v_pk_mul_f32 v[44:45], v[44:45], v[118:119] op_sel_hi:[1,0]
	v_pk_mul_f32 v[46:47], v[46:47], v[118:119] op_sel_hi:[1,0]
	v_pk_mul_f32 v[48:49], v[48:49], v[118:119] op_sel_hi:[1,0]
	v_div_fixup_f32 v118, v123, v125, 1.0
	v_div_fmas_f32 v123, v128, v135, v144
	s_mov_b64 vcc, s[8:9]
	v_fma_f32 v150, -v139, v152, v140
	v_fma_f32 v126, -v137, v151, v138
	v_pk_mul_f32 v[48:49], v[4:5], v[48:49]
	v_pk_mul_f32 v[56:57], v[56:57], v[118:119] op_sel_hi:[1,0]
	v_pk_mul_f32 v[58:59], v[58:59], v[118:119] op_sel_hi:[1,0]
	v_pk_mul_f32 v[60:61], v[60:61], v[118:119] op_sel_hi:[1,0]
	v_pk_mul_f32 v[62:63], v[62:63], v[118:119] op_sel_hi:[1,0]
	v_div_fixup_f32 v118, v123, v119, 1.0
	v_div_fmas_f32 v119, v129, v136, v148
	s_mov_b64 vcc, s[12:13]
	v_fmac_f32_e32 v152, v150, v143
	v_pk_mul_f32 v[44:45], v[8:9], v[44:45]
	v_pk_mul_f32 v[42:43], v[6:7], v[42:43]
	v_pk_mul_f32 v[46:47], v[2:3], v[46:47]
	v_mul_f32_e32 v116, v48, v116
	v_mul_f32_e32 v117, v49, v117
	v_pk_mul_f32 v[48:49], v[2:3], v[60:61]
	v_pk_mul_f32 v[38:39], v[38:39], v[118:119] op_sel_hi:[1,0]
	v_div_fixup_f32 v60, v119, v120, 1.0
	v_div_fmas_f32 v61, v126, v142, v151
	v_fma_f32 v127, -v139, v152, v140
	v_mul_f32_e32 v110, v42, v110
	v_mul_f32_e32 v111, v43, v111
	v_mul_f32_e32 v112, v44, v112
	v_mul_f32_e32 v113, v45, v113
	v_mul_f32_e32 v114, v46, v114
	v_mul_f32_e32 v115, v47, v115
	v_pk_mul_f32 v[42:43], v[8:9], v[58:59]
	v_pk_mul_f32 v[44:45], v[6:7], v[56:57]
	v_pk_mul_f32 v[46:47], v[4:5], v[62:63]
	v_pk_mul_f32 v[56:57], v[34:35], v[118:119] op_sel_hi:[1,0]
	v_pk_mul_f32 v[58:59], v[36:37], v[118:119] op_sel_hi:[1,0]
	v_pk_mul_f32 v[40:41], v[40:41], v[118:119] op_sel_hi:[1,0]
	v_pk_mul_f32 v[38:39], v[2:3], v[38:39]
	v_pk_mul_f32 v[22:23], v[22:23], v[60:61] op_sel_hi:[1,0]
	s_mov_b64 vcc, s[0:1]
	v_cvt_pk_bf16_f32 v34, v110, v111
	v_cvt_pk_bf16_f32 v35, v112, v113
	v_cvt_pk_bf16_f32 v36, v114, v115
	v_cvt_pk_bf16_f32 v37, v116, v117
	v_mul_f32_e32 v62, v44, v102
	v_mul_f32_e32 v63, v45, v103
	v_mul_f32_e32 v102, v42, v104
	v_mul_f32_e32 v103, v43, v105
	v_mul_f32_e32 v104, v48, v106
	v_mul_f32_e32 v105, v49, v107
	v_mul_f32_e32 v106, v46, v108
	v_mul_f32_e32 v107, v47, v109
	v_pk_mul_f32 v[42:43], v[8:9], v[58:59]
	v_pk_mul_f32 v[44:45], v[6:7], v[56:57]
	v_pk_mul_f32 v[40:41], v[4:5], v[40:41]
	v_pk_mul_f32 v[46:47], v[18:19], v[60:61] op_sel_hi:[1,0]
	v_pk_mul_f32 v[48:49], v[20:21], v[60:61] op_sel_hi:[1,0]
	v_pk_mul_f32 v[24:25], v[24:25], v[60:61] op_sel_hi:[1,0]
	v_div_fixup_f32 v56, v61, v121, 1.0
	v_div_fmas_f32 v57, v127, v143, v152
	global_store_dwordx4 v130, v[34:37], s[28:29]
	v_cvt_pk_bf16_f32 v18, v62, v63
	v_cvt_pk_bf16_f32 v19, v102, v103
	v_cvt_pk_bf16_f32 v20, v104, v105
	v_mul_f32_e32 v39, v39, v99
	v_pk_mul_f32 v[22:23], v[2:3], v[22:23]
	v_cvt_pk_bf16_f32 v21, v106, v107
	v_mul_f32_e32 v44, v44, v94
	v_mul_f32_e32 v45, v45, v95
	v_mul_f32_e32 v42, v42, v96
	v_mul_f32_e32 v43, v43, v97
	v_mul_f32_e32 v58, v38, v98
	v_mul_f32_e32 v40, v40, v100
	v_mul_f32_e32 v41, v41, v101
	v_pk_mul_f32 v[34:35], v[8:9], v[48:49]
	v_pk_mul_f32 v[36:37], v[6:7], v[46:47]
	v_pk_mul_f32 v[24:25], v[4:5], v[24:25]
	v_pk_mul_f32 v[26:27], v[26:27], v[56:57] op_sel_hi:[1,0]
	v_pk_mul_f32 v[28:29], v[28:29], v[56:57] op_sel_hi:[1,0]
	v_pk_mul_f32 v[30:31], v[30:31], v[56:57] op_sel_hi:[1,0]
	v_pk_mul_f32 v[32:33], v[32:33], v[56:57] op_sel_hi:[1,0]
	v_div_fixup_f32 v38, v57, v122, 1.0
	global_store_dwordx4 v130, v[18:21], s[28:29] offset:1024
	v_mul_f32_e32 v36, v36, v86
	v_mul_f32_e32 v37, v37, v87
	v_cvt_pk_bf16_f32 v18, v44, v45
	v_cvt_pk_bf16_f32 v19, v42, v43
	v_cvt_pk_bf16_f32 v20, v58, v39
	v_mul_f32_e32 v39, v22, v90
	v_cvt_pk_bf16_f32 v21, v40, v41
	v_mul_f32_e32 v34, v34, v88
	v_mul_f32_e32 v35, v35, v89
	v_mul_f32_e32 v40, v23, v91
	v_mul_f32_e32 v41, v24, v92
	v_mul_f32_e32 v42, v25, v93
	v_pk_mul_f32 v[22:23], v[8:9], v[28:29]
	v_pk_mul_f32 v[24:25], v[6:7], v[26:27]
	v_pk_mul_f32 v[26:27], v[4:5], v[32:33]
	v_pk_mul_f32 v[28:29], v[2:3], v[30:31]
	v_pk_mul_f32 v[30:31], v[10:11], v[38:39] op_sel_hi:[1,0]
	v_pk_mul_f32 v[32:33], v[12:13], v[38:39] op_sel_hi:[1,0]
	v_pk_mul_f32 v[14:15], v[14:15], v[38:39] op_sel_hi:[1,0]
	v_pk_mul_f32 v[16:17], v[16:17], v[38:39] op_sel_hi:[1,0]
	global_store_dwordx4 v130, v[18:21], s[28:29] offset:2048
	v_cvt_pk_bf16_f32 v10, v36, v37
	v_cvt_pk_bf16_f32 v11, v34, v35
	v_cvt_pk_bf16_f32 v12, v39, v40
	v_cvt_pk_bf16_f32 v13, v41, v42
	v_mul_f32_e32 v24, v24, v78
	v_mul_f32_e32 v25, v25, v79
	v_mul_f32_e32 v22, v22, v80
	v_mul_f32_e32 v23, v23, v81
	v_mul_f32_e32 v28, v28, v82
	v_mul_f32_e32 v29, v29, v83
	v_mul_f32_e32 v26, v26, v84
	v_mul_f32_e32 v27, v27, v85
	v_pk_mul_f32 v[18:19], v[8:9], v[32:33]
	v_pk_mul_f32 v[20:21], v[6:7], v[30:31]
	v_pk_mul_f32 v[16:17], v[4:5], v[16:17]
	v_pk_mul_f32 v[14:15], v[2:3], v[14:15]
	global_store_dwordx4 v130, v[10:13], s[28:29] offset:3072
	v_mul_f32_e32 v20, v20, v70
	v_mul_f32_e32 v21, v21, v71
	v_cvt_pk_bf16_f32 v10, v24, v25
	v_cvt_pk_bf16_f32 v11, v22, v23
	v_cvt_pk_bf16_f32 v12, v28, v29
	v_cvt_pk_bf16_f32 v13, v26, v27
	v_mul_f32_e32 v18, v18, v72
	v_mul_f32_e32 v19, v19, v73
	v_mul_f32_e32 v14, v14, v74
	v_mul_f32_e32 v15, v15, v75
	v_mul_f32_e32 v16, v16, v76
	v_mul_f32_e32 v17, v17, v77
	global_store_dwordx4 v[54:55], v[10:13], off
	s_nop 1
	v_cvt_pk_bf16_f32 v10, v20, v21
	v_cvt_pk_bf16_f32 v11, v18, v19
	v_cvt_pk_bf16_f32 v12, v14, v15
	v_cvt_pk_bf16_f32 v13, v16, v17
	global_store_dwordx4 v[54:55], v[10:13], off offset:1024
	s_cbranch_scc1 .LBB0_1595

.LBB0_1650:
	s_and_b32 s0, s42, 0xfffffc00
	s_ashr_i32 s1, s0, 31
	s_ashr_i32 s44, s42, 10
	s_and_b32 s46, s38, 0xffc
	s_lshl_b64 s[18:19], s[0:1], 1
	s_cmp_lg_u32 s46, 0
	s_cselect_b64 s[26:27], -1, 0
	s_sub_i32 s45, 0x2000, s46
	s_cmp_eq_u32 s46, 0
	s_cselect_b64 s[0:1], -1, 0
	s_and_b64 s[0:1], s[0:1], exec
	s_waitcnt vmcnt(0)
	v_lshl_add_u64 v[2:3], v[130:131], 0, s[18:19]
	s_cselect_b32 s22, 0, s45
	s_lshl_b32 s12, s46, 12
	v_lshl_add_u64 v[4:5], v[2:3], 0, s[12:13]
	s_add_u32 s12, s10, s12
	s_addc_u32 s21, s11, 0
	s_add_u32 s20, s12, s18
	s_mul_hi_i32 s43, s44, 0x2100
	s_mulk_i32 s44, 0x2100
	s_addc_u32 s21, s21, s19
	v_lshl_add_u64 v[6:7], s[20:21], 0, v[128:129]
	s_add_u32 s20, s44, s46
	s_addc_u32 s21, s43, 0
	s_lshl_b64 s[34:35], s[20:21], 13
	s_add_u32 s20, s8, s34
	s_addc_u32 s21, s9, s35
	v_lshl_add_u64 v[10:11], s[20:21], 0, v[128:129]
	s_add_u32 s20, s44, s22
	s_addc_u32 s21, s43, 0
	s_lshl_b64 s[20:21], s[20:21], 13
	global_load_dwordx4 v[98:101], v[4:5], off offset:16 nt
	global_load_dwordx4 v[114:117], v[4:5], off nt
	v_add_co_u32_e32 v4, vcc, s40, v6
	s_add_u32 s20, s8, s20
	s_nop 0
	v_addc_co_u32_e32 v5, vcc, 0, v7, vcc
	v_lshl_add_u64 v[8:9], v[6:7], 0, s[14:15]
	s_addc_u32 s21, s9, s21
	v_add_co_u32_e32 v6, vcc, s41, v10
	v_lshl_add_u64 v[14:15], s[20:21], 0, v[128:129]
	s_nop 0
	v_addc_co_u32_e32 v7, vcc, 0, v11, vcc
	s_or_b32 s22, s46, 1
	v_lshl_add_u64 v[12:13], v[10:11], 0, s[16:17]
	global_load_dwordx4 v[110:113], v[8:9], off offset:16 nt
	global_load_dwordx4 v[106:109], v[12:13], off offset:16 nt
	v_add_co_u32_e32 v8, vcc, s41, v14
	s_sub_i32 s23, 0x2000, s22
	s_lshl_b32 s12, s22, 12
	v_lshl_add_u64 v[16:17], v[14:15], 0, s[16:17]
	v_addc_co_u32_e32 v9, vcc, 0, v15, vcc
	global_load_dwordx4 v[122:125], v[6:7], off offset:2048 nt
	global_load_dwordx4 v[118:121], v[8:9], off offset:2048 nt
	global_load_dwordx4 v[136:139], v[4:5], off nt
	global_load_dwordx4 v[102:105], v[16:17], off offset:16 nt
	v_lshl_add_u64 v[4:5], v[2:3], 0, s[12:13]
	s_add_u32 s12, s10, s12
	s_addc_u32 s21, s11, 0
	s_add_u32 s20, s12, s18
	s_addc_u32 s21, s21, s19
	v_lshl_add_u64 v[6:7], s[20:21], 0, v[128:129]
	s_add_u32 s20, s44, s22
	s_addc_u32 s21, s43, 0
	s_lshl_b64 s[28:29], s[20:21], 13
	s_add_u32 s20, s8, s28
	s_addc_u32 s21, s9, s29
	v_lshl_add_u64 v[10:11], s[20:21], 0, v[128:129]
	s_add_u32 s20, s44, s23
	s_addc_u32 s21, s43, 0
	s_lshl_b64 s[30:31], s[20:21], 13
	global_load_dwordx4 v[66:69], v[4:5], off offset:16 nt
	global_load_dwordx4 v[82:85], v[4:5], off nt
	v_add_co_u32_e32 v4, vcc, s40, v6
	s_add_u32 s20, s8, s30
	s_nop 0
	v_addc_co_u32_e32 v5, vcc, 0, v7, vcc
	v_lshl_add_u64 v[8:9], v[6:7], 0, s[14:15]
	s_addc_u32 s21, s9, s31
	v_add_co_u32_e32 v6, vcc, s41, v10
	v_lshl_add_u64 v[14:15], s[20:21], 0, v[128:129]
	s_nop 0
	v_addc_co_u32_e32 v7, vcc, 0, v11, vcc
	s_or_b32 s22, s46, 2
	v_lshl_add_u64 v[12:13], v[10:11], 0, s[16:17]
	global_load_dwordx4 v[78:81], v[8:9], off offset:16 nt
	global_load_dwordx4 v[74:77], v[12:13], off offset:16 nt
	v_add_co_u32_e32 v8, vcc, s41, v14
	s_sub_i32 s24, 0x2000, s22
	s_lshl_b32 s12, s22, 12
	v_lshl_add_u64 v[16:17], v[14:15], 0, s[16:17]
	v_addc_co_u32_e32 v9, vcc, 0, v15, vcc
	global_load_dwordx4 v[90:93], v[6:7], off offset:2048 nt
	global_load_dwordx4 v[86:89], v[8:9], off offset:2048 nt
	global_load_dwordx4 v[94:97], v[4:5], off nt
	global_load_dwordx4 v[70:73], v[16:17], off offset:16 nt
	v_lshl_add_u64 v[4:5], v[2:3], 0, s[12:13]
	s_add_u32 s12, s10, s12
	s_addc_u32 s21, s11, 0
	s_add_u32 s20, s12, s18
	s_addc_u32 s21, s21, s19
	v_lshl_add_u64 v[6:7], s[20:21], 0, v[128:129]
	s_add_u32 s20, s44, s22
	s_addc_u32 s21, s43, 0
	s_lshl_b64 s[22:23], s[20:21], 13
	s_add_u32 s20, s8, s22
	s_addc_u32 s21, s9, s23
	v_lshl_add_u64 v[10:11], s[20:21], 0, v[128:129]
	s_add_u32 s20, s44, s24
	s_addc_u32 s21, s43, 0
	s_lshl_b64 s[24:25], s[20:21], 13
	global_load_dwordx4 v[34:37], v[4:5], off offset:16 nt
	global_load_dwordx4 v[50:53], v[4:5], off nt
	v_add_co_u32_e32 v4, vcc, s40, v6
	s_add_u32 s20, s8, s24
	s_nop 0
	v_addc_co_u32_e32 v5, vcc, 0, v7, vcc
	v_lshl_add_u64 v[8:9], v[6:7], 0, s[14:15]
	s_addc_u32 s21, s9, s25
	v_add_co_u32_e32 v6, vcc, s41, v10
	v_lshl_add_u64 v[14:15], s[20:21], 0, v[128:129]
	s_nop 0
	v_addc_co_u32_e32 v7, vcc, 0, v11, vcc
	s_or_b32 s20, s46, 3
	v_lshl_add_u64 v[12:13], v[10:11], 0, s[16:17]
	global_load_dwordx4 v[46:49], v[8:9], off offset:16 nt
	global_load_dwordx4 v[42:45], v[12:13], off offset:16 nt
	v_add_co_u32_e32 v8, vcc, s41, v14
	s_sub_i32 s46, 0x2000, s20
	s_lshl_b32 s12, s20, 12
	v_lshl_add_u64 v[16:17], v[14:15], 0, s[16:17]
	v_addc_co_u32_e32 v9, vcc, 0, v15, vcc
	global_load_dwordx4 v[58:61], v[6:7], off offset:2048 nt
	global_load_dwordx4 v[54:57], v[8:9], off offset:2048 nt
	global_load_dwordx4 v[62:65], v[4:5], off nt
	global_load_dwordx4 v[38:41], v[16:17], off offset:16 nt
	v_lshl_add_u64 v[6:7], v[2:3], 0, s[12:13]
	s_add_u32 s12, s10, s12
	s_addc_u32 s21, s11, 0
	s_add_u32 s18, s12, s18
	s_addc_u32 s19, s21, s19
	v_lshl_add_u64 v[8:9], s[18:19], 0, v[128:129]
	s_add_u32 s18, s44, s20
	s_addc_u32 s19, s43, 0
	s_lshl_b64 s[18:19], s[18:19], 13
	s_add_u32 s20, s8, s18
	s_addc_u32 s21, s9, s19
	v_lshl_add_u64 v[12:13], s[20:21], 0, v[128:129]
	s_add_u32 s20, s44, s46
	s_addc_u32 s21, s43, 0
	s_lshl_b64 s[20:21], s[20:21], 13
	global_load_dwordx4 v[2:5], v[6:7], off offset:16 nt
	global_load_dwordx4 v[18:21], v[6:7], off nt
	v_add_co_u32_e32 v6, vcc, s40, v8
	s_add_u32 s46, s8, s20
	s_nop 0
	v_addc_co_u32_e32 v7, vcc, 0, v9, vcc
	v_lshl_add_u64 v[10:11], v[8:9], 0, s[14:15]
	s_addc_u32 s47, s9, s21
	v_add_co_u32_e32 v8, vcc, s41, v12
	v_lshl_add_u64 v[22:23], v[12:13], 0, s[16:17]
	v_lshl_add_u64 v[24:25], s[46:47], 0, v[128:129]
	v_addc_co_u32_e32 v9, vcc, 0, v13, vcc
	global_load_dwordx4 v[14:17], v[10:11], off offset:16 nt
	s_nop 0
	global_load_dwordx4 v[10:13], v[22:23], off offset:16 nt
	v_add_co_u32_e32 v22, vcc, s41, v24
	v_lshl_add_u64 v[132:133], v[24:25], 0, s[16:17]
	s_nop 0
	v_addc_co_u32_e32 v23, vcc, 0, v25, vcc
	global_load_dwordx4 v[26:29], v[8:9], off offset:2048 nt
	s_nop 0
	global_load_dwordx4 v[22:25], v[22:23], off offset:2048 nt
	s_nop 0
	global_load_dwordx4 v[30:33], v[6:7], off nt
	s_nop 0
	global_load_dwordx4 v[6:9], v[132:133], off offset:16 nt
	s_waitcnt vmcnt(25)
	v_lshlrev_b32_e32 v1, 16, v136
	v_lshlrev_b32_e32 v127, 16, v114
	v_and_b32_e32 v136, 0xffff0000, v136
	v_and_b32_e32 v114, 0xffff0000, v114
	v_sub_f32_e32 v140, v127, v1
	v_lshlrev_b32_e32 v141, 16, v122
	v_mul_f32_e32 v140, v140, v141
	v_sub_f32_e32 v141, v114, v136
	v_and_b32_e32 v122, 0xffff0000, v122
	v_add_f32_e32 v1, v1, v127
	v_lshlrev_b32_e32 v127, 16, v118
	v_add_f32_e32 v114, v136, v114
	v_and_b32_e32 v118, 0xffff0000, v118
	v_mul_f32_e32 v122, v141, v122
	v_mul_f32_e32 v1, v1, v127
	v_mul_f32_e32 v114, v114, v118
	v_cvt_pk_bf16_f32 v122, v140, v122
	v_cvt_pk_bf16_f32 v114, v1, v114
	v_lshlrev_b32_e32 v1, 16, v137
	v_lshlrev_b32_e32 v118, 16, v115
	v_and_b32_e32 v127, 0xffff0000, v137
	v_and_b32_e32 v115, 0xffff0000, v115
	v_sub_f32_e32 v136, v118, v1
	v_lshlrev_b32_e32 v137, 16, v123
	v_add_f32_e32 v1, v1, v118
	v_lshlrev_b32_e32 v118, 16, v119
	v_mul_f32_e32 v136, v136, v137
	v_sub_f32_e32 v137, v115, v127
	v_and_b32_e32 v123, 0xffff0000, v123
	v_mul_f32_e32 v1, v1, v118
	v_add_f32_e32 v115, v127, v115
	v_and_b32_e32 v118, 0xffff0000, v119
	v_mul_f32_e32 v123, v137, v123
	v_mul_f32_e32 v115, v115, v118
	v_cvt_pk_bf16_f32 v123, v136, v123
	v_cvt_pk_bf16_f32 v115, v1, v115
	v_lshlrev_b32_e32 v1, 16, v138
	v_lshlrev_b32_e32 v118, 16, v116
	s_add_u32 s44, s44, s45
	v_and_b32_e32 v119, 0xffff0000, v138
	v_and_b32_e32 v116, 0xffff0000, v116
	v_sub_f32_e32 v127, v118, v1
	v_lshlrev_b32_e32 v136, 16, v124
	v_add_f32_e32 v1, v1, v118
	v_lshlrev_b32_e32 v118, 16, v120
	s_addc_u32 s45, s43, 0
	v_mul_f32_e32 v127, v127, v136
	v_sub_f32_e32 v136, v116, v119
	v_and_b32_e32 v124, 0xffff0000, v124
	v_mul_f32_e32 v1, v1, v118
	v_add_f32_e32 v116, v119, v116
	v_and_b32_e32 v118, 0xffff0000, v120
	s_add_u32 s34, s6, s34
	v_mul_f32_e32 v124, v136, v124
	v_mul_f32_e32 v116, v116, v118
	s_addc_u32 s35, s7, s35
	v_cvt_pk_bf16_f32 v124, v127, v124
	v_cvt_pk_bf16_f32 v116, v1, v116
	v_lshlrev_b32_e32 v1, 16, v139
	v_lshlrev_b32_e32 v118, 16, v117
	v_lshl_add_u64 v[134:135], s[34:35], 0, v[128:129]
	s_lshl_b64 s[34:35], s[44:45], 13
	v_and_b32_e32 v119, 0xffff0000, v139
	v_and_b32_e32 v117, 0xffff0000, v117
	v_sub_f32_e32 v120, v118, v1
	v_lshlrev_b32_e32 v127, 16, v125
	v_add_f32_e32 v1, v1, v118
	v_lshlrev_b32_e32 v118, 16, v121
	s_add_u32 s34, s6, s34
	v_mul_f32_e32 v120, v120, v127
	v_sub_f32_e32 v127, v117, v119
	v_mul_f32_e32 v1, v1, v118
	v_add_f32_e32 v117, v119, v117
	v_and_b32_e32 v118, 0xffff0000, v121
	s_addc_u32 s35, s7, s35
	v_mul_f32_e32 v117, v117, v118
	v_add_co_u32_e32 v118, vcc, 0x1000, v134
	v_lshl_add_u64 v[132:133], s[34:35], 0, v[128:129]
	v_and_b32_e32 v125, 0xffff0000, v125
	v_addc_co_u32_e32 v119, vcc, 0, v135, vcc
	v_lshl_add_u64 v[132:133], v[132:133], 0, s[16:17]
	v_mul_f32_e32 v125, v127, v125
	s_mov_b64 vcc, s[0:1]
	v_cvt_pk_bf16_f32 v125, v120, v125
	v_cvt_pk_bf16_f32 v117, v1, v117
	global_store_dwordx4 v[118:119], v[122:125], off offset:2048
	s_cbranch_vccnz .LBB0_1652
	global_store_dwordx4 v[132:133], v[114:117], off

.LBB0_1654:
	s_cmp_lt_i32 s36, 2
	s_cbranch_scc0 .LBB0_1656
	s_mul_i32 s1, s36, 0x2100000
	s_mul_hi_i32 s0, s36, 0x2100000
	s_add_u32 s1, s1, 0x1000c00
	s_addc_u32 s0, s0, 0
	s_waitcnt vmcnt(0)
	v_mov_b32_e32 v3, s0
	s_lshl_b32 s0, s36, 10
	v_or_b32_e32 v2, s1, v126
	s_ashr_i32 s1, s0, 31
	s_lshl_b64 s[0:1], s[0:1], 2
	s_add_u32 s0, s92, s0
	s_addc_u32 s1, s93, s1
	v_lshlrev_b32_e32 v6, 2, v126
	v_mov_b32_e32 v7, 0
	v_lshlrev_b64 v[14:15], 1, v[2:3]
	v_lshl_add_u64 v[10:11], s[0:1], 0, v[6:7]
	s_mov_b32 s0, 0x300000
	v_lshl_add_u64 v[16:17], s[8:9], 0, v[14:15]
	v_add_co_u32_e32 v6, vcc, s0, v10
	s_mov_b64 s[0:1], 0x300000
	global_load_dwordx4 v[2:5], v[16:17], off nt
	v_addc_co_u32_e32 v7, vcc, 0, v11, vcc
	v_lshl_add_u64 v[18:19], v[10:11], 0, s[0:1]
	global_load_dwordx4 v[6:9], v[6:7], off nt
	v_lshl_add_u64 v[14:15], s[6:7], 0, v[14:15]
	global_load_dwordx4 v[10:13], v[18:19], off offset:16 nt
	s_waitcnt vmcnt(2)
	v_lshlrev_b32_e32 v1, 16, v2
	v_and_b32_e32 v2, 0xffff0000, v2
	v_lshlrev_b32_e32 v20, 16, v3
	v_and_b32_e32 v3, 0xffff0000, v3
	v_lshlrev_b32_e32 v21, 16, v4
	v_and_b32_e32 v4, 0xffff0000, v4
	v_lshlrev_b32_e32 v22, 16, v5
	v_and_b32_e32 v5, 0xffff0000, v5
	s_waitcnt vmcnt(1)
	v_mul_f32_e32 v1, v6, v1
	v_mul_f32_e32 v2, v7, v2
	v_mul_f32_e32 v6, v8, v20
	v_mul_f32_e32 v3, v9, v3
	s_waitcnt vmcnt(0)
	v_mul_f32_e32 v7, v10, v21
	v_mul_f32_e32 v4, v11, v4
	v_mul_f32_e32 v8, v12, v22
	v_mul_f32_e32 v5, v13, v5
	v_cvt_pk_bf16_f32 v2, v1, v2
	v_cvt_pk_bf16_f32 v3, v6, v3
	v_cvt_pk_bf16_f32 v4, v7, v4
	v_cvt_pk_bf16_f32 v5, v8, v5
	global_load_dwordx4 v[6:9], v[16:17], off offset:16 nt
	s_waitcnt vmcnt(0)
	v_lshlrev_b32_e32 v1, 16, v6
	global_store_dwordx4 v[14:15], v[2:5], off
	global_load_dwordx4 v[2:5], v[18:19], off offset:32 nt
	s_nop 0
	global_load_dwordx4 v[10:13], v[18:19], off offset:48 nt
	v_and_b32_e32 v6, 0xffff0000, v6
	v_lshlrev_b32_e32 v16, 16, v7
	v_and_b32_e32 v7, 0xffff0000, v7
	v_lshlrev_b32_e32 v17, 16, v8
	v_and_b32_e32 v8, 0xffff0000, v8
	v_lshlrev_b32_e32 v18, 16, v9
	v_and_b32_e32 v9, 0xffff0000, v9
	s_waitcnt vmcnt(1)
	v_mul_f32_e32 v1, v2, v1
	v_mul_f32_e32 v2, v3, v6
	v_mul_f32_e32 v3, v4, v16
	v_mul_f32_e32 v4, v5, v7
	s_waitcnt vmcnt(0)
	v_mul_f32_e32 v5, v10, v17
	v_mul_f32_e32 v6, v11, v8
	v_mul_f32_e32 v7, v12, v18
	v_mul_f32_e32 v8, v13, v9
	v_cvt_pk_bf16_f32 v2, v1, v2
	v_cvt_pk_bf16_f32 v3, v3, v4
	v_cvt_pk_bf16_f32 v4, v5, v6
	v_cvt_pk_bf16_f32 v5, v7, v8
	global_store_dwordx4 v[14:15], v[2:5], off offset:16
